# v10 without the per-cluster s_setprio toggles
# baseline (speedup 1.0000x reference)
; #define MFMA(a, b, c) __builtin_amdgcn_mfma_f32_32x32x16_bf16((a), (b), (c), 0, 0, 0)
; template <int N> DI void lgkm_wait() { asm volatile("s_waitcnt lgkmcnt(%0)" :: "i"(N) : "memory"); }
; #define SBAR() __builtin_amdgcn_sched_barrier(0)
;   static DI void run(unsigned vaddr, s16x4 (&lo)[R], s16x4 (&hi)[R], const f32x16& p0, const f32x16& p1, bf16x8& pfc, f32x16 (&o)[4]) {
;     constexpr int issued = (J + R < NF) ? (J + R) : NF;
;     if constexpr ((J & 3) == 0) {
;       if constexpr ((J >> 2) == 0) pfc = pack8<0>(p0);
;       else if constexpr ((J >> 2) == 1) pfc = pack8<8>(p0);
;       else if constexpr ((J >> 2) == 2) pfc = pack8<0>(p1);
;       else pfc = pack8<8>(p1);
;     }
;     lgkm_wait<2 * (issued - J - 1)>(); SBAR();
;     o[J & 3] = MFMA(__builtin_shufflevector(lo[J % R], hi[J % R], 0, 1, 2, 3, 4, 5, 6, 7), pfc, o[J & 3]);
;     SBAR();
;     if (J + R < NF) {
;       constexpr int off = ((J + R) & 3) * 32 * 136 + ((J + R) >> 2) * 32;
;       lo[J % R] = lds_rd64<off>(vaddr); hi[J % R] = lds_rd64<off + 16>(vaddr); SBAR();
;     }
;     if constexpr (J + 1 < NF) PvStep<J + 1, NF, R>::run(vaddr, lo, hi, p0, p1, pfc, o);
;   }
; template <int DQK, int MODE, bool PIPE>
; DI void attn_core(const u16* __restrict__ Qg, const u16* __restrict__ Kg, const u16* __restrict__ Vtg, int ntiles,
;                   int kr_lo, int rs, int r_q, int c_q, int cs, const float* biasL, char* lds, f32x16 (&o)[4], float& l_out, int tid) {
;     ...
;     for (int i = 0; i < 16; ++i) { p0[i] = __builtin_amdgcn_exp2f(p0[i]); p1[i] = __builtin_amdgcn_exp2f(p1[i]); ps += p0[i] + p1[i]; }
;     l += ps;
;     const char* vb = lds + (t & 1) * A_BUF + A_VOFF + r32 * 136 + h * 8;
;     {
;       bf16x8 pfc;
;       constexpr int R = PV_RING;
;       const unsigned vaddr = (unsigned)(size_t)vb;
;       s16x4 vlo[R], vhi[R];
;       SBAR();
;       vlo[0] = lds_rd64<0>(vaddr); vhi[0] = lds_rd64<16>(vaddr);
;       vlo[1] = lds_rd64<32 * 136>(vaddr); vhi[1] = lds_rd64<32 * 136 + 16>(vaddr);
;       if (R > 2) { vlo[2 % R] = lds_rd64<64 * 136>(vaddr); vhi[2 % R] = lds_rd64<64 * 136 + 16>(vaddr); }
;       if (R > 3) { vlo[3 % R] = lds_rd64<96 * 136>(vaddr); vhi[3 % R] = lds_rd64<96 * 136 + 16>(vaddr); }
;       SBAR();
;       __builtin_amdgcn_s_setprio(1);
;       PvStep<0, 16, R>::run(vaddr, vlo, vhi, p0, p1, pfc, o);
;       __builtin_amdgcn_s_setprio(0);
.LBB0_724:
	s_nop 0
	v_exp_f32_e32 v87, v2
	s_nop 1
	v_exp_f32_e32 v103, v18
	v_exp_f32_e32 v88, v3
	v_exp_f32_e32 v104, v19
	v_exp_f32_e32 v89, v4
	v_exp_f32_e32 v105, v20
	v_exp_f32_e32 v90, v5
	v_exp_f32_e32 v106, v21
	v_exp_f32_e32 v91, v6
	v_exp_f32_e32 v107, v22
	v_exp_f32_e32 v92, v7
	v_exp_f32_e32 v108, v23
	v_exp_f32_e32 v93, v8
	v_exp_f32_e32 v109, v24
	v_exp_f32_e32 v94, v9
	v_exp_f32_e32 v110, v25
	v_exp_f32_e32 v95, v10
	v_exp_f32_e32 v111, v26
	v_exp_f32_e32 v96, v11
	v_exp_f32_e32 v112, v27
	v_exp_f32_e32 v97, v12
	v_exp_f32_e32 v113, v28
	v_exp_f32_e32 v98, v13
	v_exp_f32_e32 v114, v29
	v_exp_f32_e32 v99, v14
	v_exp_f32_e32 v115, v30
	v_exp_f32_e32 v100, v15
	v_exp_f32_e32 v116, v31
	v_exp_f32_e32 v101, v16
	v_exp_f32_e32 v117, v32
	v_exp_f32_e32 v102, v17
	v_exp_f32_e32 v118, v33
	s_movk_i32 s8, 0xff78
	v_lshlrev_b32_e32 v239, 3, v195
	v_mad_i32_i24 v2, v193, s8, v34
	v_mov_b32_e32 v67, v66
	v_mov_b32_e32 v68, v66
	v_mov_b32_e32 v69, v66
	v_mov_b32_e32 v70, v66
	v_mov_b32_e32 v71, v66
	v_mov_b32_e32 v72, v66
	v_mov_b32_e32 v73, v66
	v_mov_b32_e32 v74, v66
	v_mov_b32_e32 v75, v66
	v_mov_b32_e32 v76, v66
	v_mov_b32_e32 v77, v66
	v_mov_b32_e32 v78, v66
	v_mov_b32_e32 v79, v66
	v_mov_b32_e32 v80, v66
	v_mov_b32_e32 v81, v66
	v_add3_u32 v119, v2, v239, s33
	ds_read_b64 v[2:3], v119 offset:0
	ds_read_b64 v[4:5], v119 offset:16
	ds_read_b64 v[6:7], v119 offset:0x1100
	ds_read_b64 v[8:9], v119 offset:0x1110
	ds_read_b64 v[10:11], v119 offset:0x2200
	ds_read_b64 v[12:13], v119 offset:0x2210
	ds_read_b64 v[120:121], v119 offset:0x3300
	ds_read_b64 v[122:123], v119 offset:0x3310
	s_waitcnt lgkmcnt(6)
	v_cvt_pk_bf16_f32 v124, v87, v88
	v_cvt_pk_bf16_f32 v125, v89, v90
	v_cvt_pk_bf16_f32 v126, v91, v92
	v_cvt_pk_bf16_f32 v127, v93, v94
	s_nop 1
	v_mfma_f32_32x32x16_bf16 v[50:65], v[2:5], v[124:127], v[66:81]
	ds_read_b64 v[240:241], v119 offset:32
	ds_read_b64 v[242:243], v119 offset:48
	s_waitcnt lgkmcnt(6)
	v_mfma_f32_32x32x16_bf16 v[34:49], v[6:9], v[124:127], v[66:81]
	ds_read_b64 v[244:245], v119 offset:0x1120
	ds_read_b64 v[246:247], v119 offset:0x1130
	s_waitcnt lgkmcnt(6)
	v_mfma_f32_32x32x16_bf16 v[18:33], v[10:13], v[124:127], v[66:81]
	ds_read_b64 v[248:249], v119 offset:0x2220
	ds_read_b64 v[250:251], v119 offset:0x2230
	s_waitcnt lgkmcnt(6)
	v_mov_b64_e32 v[2:3], v[66:67]
	v_mov_b64_e32 v[4:5], v[68:69]
	v_mov_b64_e32 v[6:7], v[70:71]
	v_mov_b64_e32 v[8:9], v[72:73]
	v_mov_b64_e32 v[10:11], v[74:75]
	v_mov_b64_e32 v[12:13], v[76:77]
	v_mov_b64_e32 v[14:15], v[78:79]
	v_mov_b64_e32 v[16:17], v[80:81]
	s_nop 1
	v_mfma_f32_32x32x16_bf16 v[2:17], v[120:123], v[124:127], v[2:17]
	ds_read_b64 v[68:69], v119 offset:0x3320
	ds_read_b64 v[70:71], v119 offset:0x3330
	s_waitcnt lgkmcnt(6)
	v_cvt_pk_bf16_f32 v72, v95, v96
	v_cvt_pk_bf16_f32 v73, v97, v98
	v_cvt_pk_bf16_f32 v74, v99, v100
	v_cvt_pk_bf16_f32 v75, v101, v102
	s_nop 1
	v_mfma_f32_32x32x16_bf16 v[50:65], v[240:243], v[72:75], v[50:65]
	ds_read_b64 v[76:77], v119 offset:64
	ds_read_b64 v[78:79], v119 offset:0x50
	s_waitcnt lgkmcnt(6)
	v_mfma_f32_32x32x16_bf16 v[34:49], v[244:247], v[72:75], v[34:49]
	ds_read_b64 v[120:121], v119 offset:0x1140
	ds_read_b64 v[122:123], v119 offset:0x1150
	s_waitcnt lgkmcnt(6)
	v_mfma_f32_32x32x16_bf16 v[18:33], v[248:251], v[72:75], v[18:33]
	ds_read_b64 v[124:125], v119 offset:0x2240
	ds_read_b64 v[126:127], v119 offset:0x2250
	s_waitcnt lgkmcnt(6)
	v_mfma_f32_32x32x16_bf16 v[2:17], v[68:71], v[72:75], v[2:17]
	ds_read_b64 v[68:69], v119 offset:0x3340
	ds_read_b64 v[70:71], v119 offset:0x3350
	s_waitcnt lgkmcnt(6)
	v_cvt_pk_bf16_f32 v72, v103, v104
	v_cvt_pk_bf16_f32 v73, v105, v106
	v_cvt_pk_bf16_f32 v74, v107, v108
	v_cvt_pk_bf16_f32 v75, v109, v110
	s_nop 1
	v_mfma_f32_32x32x16_bf16 v[50:65], v[76:79], v[72:75], v[50:65]
	ds_read_b64 v[76:77], v119 offset:0x60
	ds_read_b64 v[78:79], v119 offset:0x70
	s_waitcnt lgkmcnt(6)
	v_mfma_f32_32x32x16_bf16 v[34:49], v[120:123], v[72:75], v[34:49]
	ds_read_b64 v[120:121], v119 offset:0x1160
	ds_read_b64 v[122:123], v119 offset:0x1170
	s_waitcnt lgkmcnt(6)
	v_mfma_f32_32x32x16_bf16 v[18:33], v[124:127], v[72:75], v[18:33]
	ds_read_b64 v[124:125], v119 offset:0x2260
	ds_read_b64 v[126:127], v119 offset:0x2270
	s_waitcnt lgkmcnt(6)
	v_mfma_f32_32x32x16_bf16 v[2:17], v[68:71], v[72:75], v[2:17]
	ds_read_b64 v[68:69], v119 offset:0x3360
	ds_read_b64 v[70:71], v119 offset:0x3370
	s_waitcnt lgkmcnt(6)
	v_cvt_pk_bf16_f32 v72, v111, v112
	v_cvt_pk_bf16_f32 v73, v113, v114
	v_cvt_pk_bf16_f32 v74, v115, v116
	v_cvt_pk_bf16_f32 v75, v117, v118
	s_nop 1
	v_mfma_f32_32x32x16_bf16 v[50:65], v[76:79], v[72:75], v[50:65]
	s_waitcnt lgkmcnt(4)
	v_mfma_f32_32x32x16_bf16 v[34:49], v[120:123], v[72:75], v[34:49]
	s_waitcnt lgkmcnt(2)
	v_mfma_f32_32x32x16_bf16 v[18:33], v[124:127], v[72:75], v[18:33]
	s_waitcnt lgkmcnt(0)
	v_mfma_f32_32x32x16_bf16 v[2:17], v[68:71], v[72:75], v[2:17]
	s_and_b64 vcc, exec, s[6:7]
	s_cbranch_vccnz .LBB0_726
	s_waitcnt vmcnt(3)
	ds_write_b128 v85, v[162:165] offset:43008
	s_waitcnt vmcnt(2)
	ds_write_b128 v86, v[170:173] offset:43008

; #define MFMA(a, b, c) __builtin_amdgcn_mfma_f32_32x32x16_bf16((a), (b), (c), 0, 0, 0)
; template <int N> DI void lgkm_wait() { asm volatile("s_waitcnt lgkmcnt(%0)" :: "i"(N) : "memory"); }
; #define SBAR() __builtin_amdgcn_sched_barrier(0)
;   static DI void run(unsigned vaddr, s16x4 (&lo)[R], s16x4 (&hi)[R], const f32x16& p0, const f32x16& p1, bf16x8& pfc, f32x16 (&o)[4]) {
;     constexpr int issued = (J + R < NF) ? (J + R) : NF;
;     if constexpr ((J & 3) == 0) {
;       if constexpr ((J >> 2) == 0) pfc = pack8<0>(p0);
;       else if constexpr ((J >> 2) == 1) pfc = pack8<8>(p0);
;       else if constexpr ((J >> 2) == 2) pfc = pack8<0>(p1);
;       else pfc = pack8<8>(p1);
;     }
;     lgkm_wait<2 * (issued - J - 1)>(); SBAR();
;     o[J & 3] = MFMA(__builtin_shufflevector(lo[J % R], hi[J % R], 0, 1, 2, 3, 4, 5, 6, 7), pfc, o[J & 3]);
;     SBAR();
;     if (J + R < NF) {
;       constexpr int off = ((J + R) & 3) * 32 * 136 + ((J + R) >> 2) * 32;
;       lo[J % R] = lds_rd64<off>(vaddr); hi[J % R] = lds_rd64<off + 16>(vaddr); SBAR();
;     }
;     if constexpr (J + 1 < NF) PvStep<J + 1, NF, R>::run(vaddr, lo, hi, p0, p1, pfc, o);
;   }
; template <int DQK, int MODE, bool PIPE>
; DI void attn_core(const u16* __restrict__ Qg, const u16* __restrict__ Kg, const u16* __restrict__ Vtg, int ntiles,
;                   int kr_lo, int rs, int r_q, int c_q, int cs, const float* biasL, char* lds, f32x16 (&o)[4], float& l_out, int tid) {
;     ...
;     for (int i = 0; i < 16; ++i) { p0[i] = __builtin_amdgcn_exp2f(p0[i]); p1[i] = __builtin_amdgcn_exp2f(p1[i]); ps += p0[i] + p1[i]; }
;     l += ps;
;     const char* vb = lds + (t & 1) * A_BUF + A_VOFF + r32 * 136 + h * 8;
;     {
;       bf16x8 pfc;
;       constexpr int R = PV_RING;
;       const unsigned vaddr = (unsigned)(size_t)vb;
;       s16x4 vlo[R], vhi[R];
;       SBAR();
;       vlo[0] = lds_rd64<0>(vaddr); vhi[0] = lds_rd64<16>(vaddr);
;       vlo[1] = lds_rd64<32 * 136>(vaddr); vhi[1] = lds_rd64<32 * 136 + 16>(vaddr);
;       if (R > 2) { vlo[2 % R] = lds_rd64<64 * 136>(vaddr); vhi[2 % R] = lds_rd64<64 * 136 + 16>(vaddr); }
;       if (R > 3) { vlo[3 % R] = lds_rd64<96 * 136>(vaddr); vhi[3 % R] = lds_rd64<96 * 136 + 16>(vaddr); }
;       SBAR();
;       __builtin_amdgcn_s_setprio(1);
;       PvStep<0, 16, R>::run(vaddr, vlo, vhi, p0, p1, pfc, o);
;       __builtin_amdgcn_s_setprio(0);
.LBB0_808:
	v_exp_f32_e32 v110, v82
	v_exp_f32_e32 v111, v66
	v_exp_f32_e32 v112, v83
	v_exp_f32_e32 v113, v67
	v_exp_f32_e32 v114, v84
	v_exp_f32_e32 v115, v68
	v_exp_f32_e32 v116, v85
	v_exp_f32_e32 v117, v69
	v_add_f32_e32 v66, v111, v110
	v_add_f32_e32 v66, 0, v66
	v_add_f32_e32 v67, v113, v112
	v_add_f32_e32 v66, v67, v66
	v_add_f32_e32 v67, v115, v114
	v_add_f32_e32 v66, v67, v66
	v_add_f32_e32 v67, v117, v116
	v_add_f32_e32 v82, v67, v66
	v_exp_f32_e32 v67, v86
	v_exp_f32_e32 v69, v70
	v_exp_f32_e32 v66, v87
	v_exp_f32_e32 v68, v71
	v_pk_mov_b32 v[98:99], v[66:67], v[66:67] op_sel:[1,0]
	v_pk_add_f32 v[70:71], v[68:69], v[66:67]
	v_pk_mov_b32 v[66:67], v[68:69], v[68:69] op_sel:[1,0]
	v_add_f32_e32 v71, v71, v82
	v_add_f32_e32 v82, v70, v71
	v_exp_f32_e32 v69, v88
	v_exp_f32_e32 v71, v72
	v_exp_f32_e32 v68, v89
	v_exp_f32_e32 v70, v73
	v_pk_mov_b32 v[100:101], v[68:69], v[68:69] op_sel:[1,0]
	v_pk_add_f32 v[72:73], v[70:71], v[68:69]
	v_exp_f32_e32 v69, v90
	v_add_f32_e32 v73, v73, v82
	v_add_f32_e32 v82, v72, v73
	v_exp_f32_e32 v73, v74
	v_exp_f32_e32 v68, v91
	v_exp_f32_e32 v72, v75
	v_pk_mov_b32 v[70:71], v[70:71], v[70:71] op_sel:[1,0]
	v_pk_mov_b32 v[102:103], v[68:69], v[68:69] op_sel:[1,0]
	v_pk_add_f32 v[74:75], v[72:73], v[68:69]
	v_pk_mov_b32 v[68:69], v[72:73], v[72:73] op_sel:[1,0]
	v_add_f32_e32 v75, v75, v82
	v_add_f32_e32 v82, v74, v75
	v_exp_f32_e32 v73, v92
	v_exp_f32_e32 v75, v76
	v_exp_f32_e32 v72, v93
	v_exp_f32_e32 v74, v77
	v_pk_mov_b32 v[104:105], v[72:73], v[72:73] op_sel:[1,0]
	v_pk_add_f32 v[76:77], v[74:75], v[72:73]
	v_pk_mov_b32 v[72:73], v[74:75], v[74:75] op_sel:[1,0]
	v_add_f32_e32 v77, v77, v82
	v_add_f32_e32 v82, v76, v77
	v_exp_f32_e32 v75, v94
	v_exp_f32_e32 v77, v78
	v_exp_f32_e32 v74, v95
	v_exp_f32_e32 v76, v79
	v_pk_mov_b32 v[94:95], v[74:75], v[74:75] op_sel:[1,0]
	v_pk_add_f32 v[78:79], v[76:77], v[74:75]
	v_pk_mov_b32 v[106:107], v[76:77], v[76:77] op_sel:[1,0]
	v_exp_f32_e32 v75, v96
	v_exp_f32_e32 v77, v80
	v_exp_f32_e32 v74, v97
	v_exp_f32_e32 v76, v81
	v_add_f32_e32 v79, v79, v82
	v_add_f32_e32 v82, v78, v79
	v_pk_mov_b32 v[96:97], v[74:75], v[74:75] op_sel:[1,0]
	v_pk_add_f32 v[78:79], v[76:77], v[74:75]
	v_pk_mov_b32 v[108:109], v[76:77], v[76:77] op_sel:[1,0]
	v_add_f32_e32 v79, v79, v82
	v_add_f32_e32 v74, v78, v79
	v_add_f32_e32 v241, v241, v74
	v_add_u32_e32 v74, s16, v245
	v_add3_u32 v118, v74, v239, s33
	ds_read_b64 v[74:75], v118 offset:0
	ds_read_b64 v[76:77], v118 offset:16
	ds_read_b64 v[78:79], v118 offset:0x1100
	ds_read_b64 v[80:81], v118 offset:0x1110
	ds_read_b64 v[82:83], v118 offset:0x2200
	ds_read_b64 v[84:85], v118 offset:0x2210
	ds_read_b64 v[86:87], v118 offset:0x3300
	ds_read_b64 v[88:89], v118 offset:0x3310
	s_waitcnt lgkmcnt(6)
	v_cvt_pk_bf16_f32 v90, v110, v112
	v_cvt_pk_bf16_f32 v91, v114, v116
	v_cvt_pk_bf16_f32 v92, v98, v99
	v_cvt_pk_bf16_f32 v93, v100, v101
	s_nop 1
	v_mfma_f32_32x32x16_bf16 v[50:65], v[74:77], v[90:93], v[50:65]
	ds_read_b64 v[74:75], v118 offset:32
	ds_read_b64 v[76:77], v118 offset:48
	s_waitcnt lgkmcnt(6)
	v_mfma_f32_32x32x16_bf16 v[34:49], v[78:81], v[90:93], v[34:49]
	ds_read_b64 v[78:79], v118 offset:0x1120
	ds_read_b64 v[80:81], v118 offset:0x1130
	s_waitcnt lgkmcnt(6)
	v_mfma_f32_32x32x16_bf16 v[18:33], v[82:85], v[90:93], v[18:33]
	ds_read_b64 v[82:83], v118 offset:0x2220
	ds_read_b64 v[84:85], v118 offset:0x2230
	s_waitcnt lgkmcnt(6)
	v_mfma_f32_32x32x16_bf16 v[2:17], v[86:89], v[90:93], v[2:17]
	ds_read_b64 v[86:87], v118 offset:0x3320
	ds_read_b64 v[88:89], v118 offset:0x3330
	s_waitcnt lgkmcnt(6)
	v_cvt_pk_bf16_f32 v90, v102, v103
	v_cvt_pk_bf16_f32 v91, v104, v105
	v_cvt_pk_bf16_f32 v92, v94, v95
	v_cvt_pk_bf16_f32 v93, v96, v97
	s_nop 1
	v_mfma_f32_32x32x16_bf16 v[50:65], v[74:77], v[90:93], v[50:65]
	ds_read_b64 v[74:75], v118 offset:64
	ds_read_b64 v[76:77], v118 offset:0x50
	s_waitcnt lgkmcnt(6)
	v_mfma_f32_32x32x16_bf16 v[34:49], v[78:81], v[90:93], v[34:49]
	ds_read_b64 v[78:79], v118 offset:0x1140
	ds_read_b64 v[80:81], v118 offset:0x1150
	s_waitcnt lgkmcnt(6)
	v_mfma_f32_32x32x16_bf16 v[18:33], v[82:85], v[90:93], v[18:33]
	ds_read_b64 v[82:83], v118 offset:0x2240
	ds_read_b64 v[84:85], v118 offset:0x2250
	s_waitcnt lgkmcnt(6)
	v_mfma_f32_32x32x16_bf16 v[2:17], v[86:89], v[90:93], v[2:17]
	ds_read_b64 v[86:87], v118 offset:0x3340
	ds_read_b64 v[88:89], v118 offset:0x3350
	s_waitcnt lgkmcnt(6)
	v_cvt_pk_bf16_f32 v90, v111, v113
	v_cvt_pk_bf16_f32 v91, v115, v117
	v_cvt_pk_bf16_f32 v92, v66, v67
	v_cvt_pk_bf16_f32 v93, v70, v71
	s_nop 1
	v_mfma_f32_32x32x16_bf16 v[50:65], v[74:77], v[90:93], v[50:65]
	ds_read_b64 v[74:75], v118 offset:0x60
	ds_read_b64 v[76:77], v118 offset:0x70
	s_waitcnt lgkmcnt(6)
	v_mfma_f32_32x32x16_bf16 v[34:49], v[78:81], v[90:93], v[34:49]
	ds_read_b64 v[78:79], v118 offset:0x1160
	ds_read_b64 v[80:81], v118 offset:0x1170
	s_waitcnt lgkmcnt(6)
	v_mfma_f32_32x32x16_bf16 v[18:33], v[82:85], v[90:93], v[18:33]
	ds_read_b64 v[82:83], v118 offset:0x2260
	ds_read_b64 v[84:85], v118 offset:0x2270
	s_waitcnt lgkmcnt(6)
	v_mfma_f32_32x32x16_bf16 v[2:17], v[86:89], v[90:93], v[2:17]
	ds_read_b64 v[86:87], v118 offset:0x3360
	ds_read_b64 v[88:89], v118 offset:0x3370
	s_waitcnt lgkmcnt(6)
	v_cvt_pk_bf16_f32 v66, v68, v69
	v_cvt_pk_bf16_f32 v67, v72, v73
	v_cvt_pk_bf16_f32 v68, v106, v107
	v_cvt_pk_bf16_f32 v69, v108, v109
	s_nop 1
	v_mfma_f32_32x32x16_bf16 v[50:65], v[74:77], v[66:69], v[50:65]
	s_waitcnt lgkmcnt(4)
	v_mfma_f32_32x32x16_bf16 v[34:49], v[78:81], v[66:69], v[34:49]
	s_waitcnt lgkmcnt(2)
	v_mfma_f32_32x32x16_bf16 v[18:33], v[82:85], v[66:69], v[18:33]
	s_waitcnt lgkmcnt(0)
	v_mfma_f32_32x32x16_bf16 v[2:17], v[86:89], v[66:69], v[2:17]

; #define MFMA(a, b, c) __builtin_amdgcn_mfma_f32_32x32x16_bf16((a), (b), (c), 0, 0, 0)
; DI int crow(int i, int h) { return (i & 3) + 8 * (i >> 2) + 4 * h; }
; #define SBAR() __builtin_amdgcn_sched_barrier(0)
; template <int DQK, int MODE, bool PIPE>
; DI void attn_core(const u16* __restrict__ Qg, const u16* __restrict__ Kg, const u16* __restrict__ Vtg, int ntiles,
;                   int kr_lo, int rs, int r_q, int c_q, int cs, const float* biasL, char* lds, f32x16 (&o)[4], float& l_out, int tid) {
;     ...
;   auto qk = [&](int t, f32x16& p0, f32x16& p1) {
;     const char* kb = lds + (t & 1) * A_BUF + r32 * KSTR + h * 16;
;     if (MODE != 0) {
; #pragma unroll
;       for (int i = 0; i < 16; ++i) { p0[i] = 0.f; p1[i] = 0.f; }
;     }
;     if (MODE == 0) {
;       constexpr int R = 4, NF = 2 * NKS;
;       const unsigned kaddr = (unsigned)(size_t)kb;
;       bf16x8 f[R];
;       SBAR();
;       f[0] = lds_rd128<0>(kaddr); f[1] = lds_rd128<32 * KSTR>(kaddr); f[2] = lds_rd128<32>(kaddr); f[3] = lds_rd128<32 * KSTR + 32>(kaddr);
;       SBAR();
;       __builtin_amdgcn_s_setprio(1);
;       QkStep<DQK, 0, NF, R>::run(kaddr, f, qf, p0, p1, negm);
;       __builtin_amdgcn_s_setprio(0);
;     } else {
; #pragma unroll
;       for (int ks = 0; ks < NKS; ++ks) {
;         const bf16x8 k0 = *(const bf16x8*)(kb + ks * 32), k1 = *(const bf16x8*)(kb + 32 * KSTR + ks * 32);
;         p0 = MFMA(k0, qf[ks], p0); p1 = MFMA(k1, qf[ks], p1);
;       }
;     }
;     if (MODE == 1 && t >= 4) {
;       const int kr = kr_lo + t - 4;
;       const float* brow = biasL + (kr - r_q + 7) * 31 + 15 - c_q;
; #pragma unroll
;       for (int i = 0; i < 16; ++i) {
;         const int kc0 = crow(i, h), kc1 = 32 + kc0;
;         p0[i] = ((unsigned)(kc0 - cs) < 16u) ? p0[i] + brow[kc0] : -1e30f;
;         p1[i] = ((unsigned)(kc1 - cs) < 16u) ? p1[i] + brow[kc1] : -1e30f;
;         if ((i & 3) == 3) __builtin_amdgcn_sched_barrier(0);
;       }
;     }
;   };
;   auto sm_pv = [&](int t, f32x16& p0, f32x16& p1) {
;     asm volatile("s_nop 7\n\ts_nop 7\n\ts_nop 7" ::: "memory");
;     if (!NEGM && __any(m != 0.f)) {
; #pragma unroll
;       for (int i = 0; i < 16; ++i) {
;         asm("v_sub_f32 %0, %1, %2" : "=v"(p0[i]) : "v"(p0[i]), "v"(m));
;         asm("v_sub_f32 %0, %1, %2" : "=v"(p1[i]) : "v"(p1[i]), "v"(m));
;       }
;     }
.LBB0_821:
	s_bitcmp1_b32 s6, 0
	s_cselect_b32 s7, 0xa800, 0
	s_add_i32 s19, s7, 0
	v_add3_u32 v244, s19, v225, v0
	ds_read_b128 v[66:69], v244 offset:0
	ds_read_b128 v[82:85], v244 offset:0x3200
	ds_read_b128 v[228:231], v244 offset:32
	ds_read_b128 v[232:235], v244 offset:0x3220
	s_waitcnt lgkmcnt(2)
	v_mfma_f32_32x32x16_bf16 v[66:81], v[66:69], v[98:101], 0
	ds_read_b128 v[236:239], v244 offset:64
	v_mfma_f32_32x32x16_bf16 v[82:97], v[82:85], v[98:101], 0
	ds_read_b128 v[240:243], v244 offset:0x3240
	s_waitcnt lgkmcnt(2)
	v_mfma_f32_32x32x16_bf16 v[66:81], v[228:231], v[102:105], v[66:81]
	ds_read_b128 v[228:231], v244 offset:0x60
	v_mfma_f32_32x32x16_bf16 v[82:97], v[232:235], v[102:105], v[82:97]
	ds_read_b128 v[232:235], v244 offset:0x3260
	s_waitcnt lgkmcnt(2)
	v_mfma_f32_32x32x16_bf16 v[66:81], v[236:239], v[106:109], v[66:81]
	ds_read_b128 v[236:239], v244 offset:0x80
	v_mfma_f32_32x32x16_bf16 v[82:97], v[240:243], v[106:109], v[82:97]
	ds_read_b128 v[240:243], v244 offset:0x3280
	s_waitcnt lgkmcnt(2)
	v_mfma_f32_32x32x16_bf16 v[66:81], v[228:231], v[110:113], v[66:81]
	ds_read_b128 v[228:231], v244 offset:0xa0
	v_mfma_f32_32x32x16_bf16 v[82:97], v[232:235], v[110:113], v[82:97]
	ds_read_b128 v[232:235], v244 offset:0x32a0
	s_waitcnt lgkmcnt(2)
	v_mfma_f32_32x32x16_bf16 v[66:81], v[236:239], v[114:117], v[66:81]
	ds_read_b128 v[236:239], v244 offset:0xc0
	v_mfma_f32_32x32x16_bf16 v[82:97], v[240:243], v[114:117], v[82:97]
	ds_read_b128 v[240:243], v244 offset:0x32c0
	s_waitcnt lgkmcnt(2)
	v_mfma_f32_32x32x16_bf16 v[66:81], v[228:231], v[118:121], v[66:81]
	ds_read_b128 v[228:231], v244 offset:0xe0
	v_mfma_f32_32x32x16_bf16 v[82:97], v[232:235], v[118:121], v[82:97]
	ds_read_b128 v[232:235], v244 offset:0x32e0
	s_waitcnt lgkmcnt(2)
	v_mfma_f32_32x32x16_bf16 v[66:81], v[236:239], v[122:125], v[66:81]
	ds_read_b128 v[236:239], v244 offset:0x100
	v_mfma_f32_32x32x16_bf16 v[82:97], v[240:243], v[122:125], v[82:97]
	ds_read_b128 v[240:243], v244 offset:0x3300
	s_waitcnt lgkmcnt(2)
	v_mfma_f32_32x32x16_bf16 v[66:81], v[228:231], v[126:129], v[66:81]
	ds_read_b128 v[228:231], v244 offset:0x120
	v_mfma_f32_32x32x16_bf16 v[82:97], v[232:235], v[126:129], v[82:97]
	ds_read_b128 v[232:235], v244 offset:0x3320
	s_waitcnt lgkmcnt(2)
	v_mfma_f32_32x32x16_bf16 v[66:81], v[236:239], v[130:133], v[66:81]
	ds_read_b128 v[236:239], v244 offset:0x140
	v_mfma_f32_32x32x16_bf16 v[82:97], v[240:243], v[130:133], v[82:97]
	ds_read_b128 v[240:243], v244 offset:0x3340
	s_waitcnt lgkmcnt(2)
	v_mfma_f32_32x32x16_bf16 v[66:81], v[228:231], v[134:137], v[66:81]
	ds_read_b128 v[228:231], v244 offset:0x160
	v_mfma_f32_32x32x16_bf16 v[82:97], v[232:235], v[134:137], v[82:97]
	ds_read_b128 v[232:235], v244 offset:0x3360
	s_waitcnt lgkmcnt(2)
	v_mfma_f32_32x32x16_bf16 v[66:81], v[236:239], v[138:141], v[66:81]
	v_mfma_f32_32x32x16_bf16 v[82:97], v[240:243], v[138:141], v[82:97]
	s_waitcnt lgkmcnt(0)
	v_mfma_f32_32x32x16_bf16 v[66:81], v[228:231], v[142:145], v[66:81]
	v_mfma_f32_32x32x16_bf16 v[82:97], v[232:235], v[142:145], v[82:97]
	s_nop 7
	s_nop 7
	v_cmp_neq_f32_e32 vcc, 0, v227
	s_cbranch_vccz .LBB0_823
	v_sub_f32 v66, v66, v227
	v_sub_f32 v82, v82, v227
	v_sub_f32 v67, v67, v227
	v_sub_f32 v83, v83, v227
	v_sub_f32 v68, v68, v227
	v_sub_f32 v84, v84, v227
	v_sub_f32 v69, v69, v227
	v_sub_f32 v85, v85, v227
	v_sub_f32 v70, v70, v227
	v_sub_f32 v86, v86, v227
	v_sub_f32 v71, v71, v227
	v_sub_f32 v87, v87, v227
	v_sub_f32 v72, v72, v227
	v_sub_f32 v88, v88, v227
	v_sub_f32 v73, v73, v227
	v_sub_f32 v89, v89, v227
	v_sub_f32 v74, v74, v227
	v_sub_f32 v90, v90, v227
	v_sub_f32 v75, v75, v227
	v_sub_f32 v91, v91, v227
	v_sub_f32 v76, v76, v227
	v_sub_f32 v92, v92, v227
	v_sub_f32 v77, v77, v227
	v_sub_f32 v93, v93, v227
	v_sub_f32 v78, v78, v227
	v_sub_f32 v94, v94, v227
	v_sub_f32 v79, v79, v227
	v_sub_f32 v95, v95, v227
	v_sub_f32 v80, v80, v227
	v_sub_f32 v96, v96, v227
	v_sub_f32 v81, v81, v227
	v_sub_f32 v97, v97, v227

; #define MFMA(a, b, c) __builtin_amdgcn_mfma_f32_32x32x16_bf16((a), (b), (c), 0, 0, 0)
; template <int N> DI void lgkm_wait() { asm volatile("s_waitcnt lgkmcnt(%0)" :: "i"(N) : "memory"); }
; #define SBAR() __builtin_amdgcn_sched_barrier(0)
;   static DI void run(unsigned vaddr, s16x4 (&lo)[R], s16x4 (&hi)[R], const f32x16& p0, const f32x16& p1, bf16x8& pfc, f32x16 (&o)[4]) {
;     constexpr int issued = (J + R < NF) ? (J + R) : NF;
;     if constexpr ((J & 3) == 0) {
;       if constexpr ((J >> 2) == 0) pfc = pack8<0>(p0);
;       else if constexpr ((J >> 2) == 1) pfc = pack8<8>(p0);
;       else if constexpr ((J >> 2) == 2) pfc = pack8<0>(p1);
;       else pfc = pack8<8>(p1);
;     }
;     lgkm_wait<2 * (issued - J - 1)>(); SBAR();
;     o[J & 3] = MFMA(__builtin_shufflevector(lo[J % R], hi[J % R], 0, 1, 2, 3, 4, 5, 6, 7), pfc, o[J & 3]);
;     SBAR();
;     if (J + R < NF) {
;       constexpr int off = ((J + R) & 3) * 32 * 136 + ((J + R) >> 2) * 32;
;       lo[J % R] = lds_rd64<off>(vaddr); hi[J % R] = lds_rd64<off + 16>(vaddr); SBAR();
;     }
;     if constexpr (J + 1 < NF) PvStep<J + 1, NF, R>::run(vaddr, lo, hi, p0, p1, pfc, o);
;   }
; template <int DQK, int MODE, bool PIPE>
; DI void attn_core(const u16* __restrict__ Qg, const u16* __restrict__ Kg, const u16* __restrict__ Vtg, int ntiles,
;                   int kr_lo, int rs, int r_q, int c_q, int cs, const float* biasL, char* lds, f32x16 (&o)[4], float& l_out, int tid) {
;     ...
;     for (int i = 0; i < 16; ++i) { p0[i] = __builtin_amdgcn_exp2f(p0[i]); p1[i] = __builtin_amdgcn_exp2f(p1[i]); ps += p0[i] + p1[i]; }
;     l += ps;
;     const char* vb = lds + (t & 1) * A_BUF + A_VOFF + r32 * 136 + h * 8;
;     {
;       bf16x8 pfc;
;       constexpr int R = PV_RING;
;       const unsigned vaddr = (unsigned)(size_t)vb;
;       s16x4 vlo[R], vhi[R];
;       SBAR();
;       vlo[0] = lds_rd64<0>(vaddr); vhi[0] = lds_rd64<16>(vaddr);
;       vlo[1] = lds_rd64<32 * 136>(vaddr); vhi[1] = lds_rd64<32 * 136 + 16>(vaddr);
;       if (R > 2) { vlo[2 % R] = lds_rd64<64 * 136>(vaddr); vhi[2 % R] = lds_rd64<64 * 136 + 16>(vaddr); }
;       if (R > 3) { vlo[3 % R] = lds_rd64<96 * 136>(vaddr); vhi[3 % R] = lds_rd64<96 * 136 + 16>(vaddr); }
;       SBAR();
;       __builtin_amdgcn_s_setprio(1);
;       PvStep<0, 16, R>::run(vaddr, vlo, vhi, p0, p1, pfc, o);
;       __builtin_amdgcn_s_setprio(0);
.LBB0_825:
	v_exp_f32_e32 v66, v66
	v_exp_f32_e32 v82, v82
	v_exp_f32_e32 v67, v67
	v_exp_f32_e32 v83, v83
	v_exp_f32_e32 v68, v68
	v_exp_f32_e32 v84, v84
	v_exp_f32_e32 v69, v69
	v_exp_f32_e32 v85, v85
	v_exp_f32_e32 v70, v70
	v_exp_f32_e32 v86, v86
	v_exp_f32_e32 v71, v71
	v_exp_f32_e32 v87, v87
	v_exp_f32_e32 v72, v72
	v_exp_f32_e32 v88, v88
	v_exp_f32_e32 v73, v73
	v_exp_f32_e32 v89, v89
	v_exp_f32_e32 v74, v74
	v_exp_f32_e32 v90, v90
	v_exp_f32_e32 v75, v75
	v_exp_f32_e32 v91, v91
	v_exp_f32_e32 v76, v76
	v_exp_f32_e32 v92, v92
	v_exp_f32_e32 v77, v77
	v_exp_f32_e32 v93, v93
	v_exp_f32_e32 v78, v78
	v_exp_f32_e32 v94, v94
	v_exp_f32_e32 v79, v79
	v_exp_f32_e32 v95, v95
	v_exp_f32_e32 v80, v80
	v_exp_f32_e32 v96, v96
	v_exp_f32_e32 v81, v81
	v_exp_f32_e32 v97, v97
	v_add_u32_e32 v228, s19, v226
	v_add3_u32 v248, v228, v168, s33
	ds_read_b64 v[228:229], v248 offset:0
	ds_read_b64 v[230:231], v248 offset:16
	ds_read_b64 v[232:233], v248 offset:0x1100
	ds_read_b64 v[234:235], v248 offset:0x1110
	ds_read_b64 v[236:237], v248 offset:0x2200
	ds_read_b64 v[238:239], v248 offset:0x2210
	ds_read_b64 v[240:241], v248 offset:0x3300
	ds_read_b64 v[242:243], v248 offset:0x3310
	s_waitcnt lgkmcnt(4)
	v_cvt_pk_bf16_f32 v244, v66, v67
	v_cvt_pk_bf16_f32 v245, v68, v69
	v_cvt_pk_bf16_f32 v246, v70, v71
	v_cvt_pk_bf16_f32 v247, v72, v73
	s_nop 1
	v_mfma_f32_32x32x16_bf16 v[50:65], v[228:231], v[244:247], v[50:65]
	ds_read_b64 v[228:229], v248 offset:32
	ds_read_b64 v[230:231], v248 offset:48
	v_mfma_f32_32x32x16_bf16 v[34:49], v[232:235], v[244:247], v[34:49]
	ds_read_b64 v[232:233], v248 offset:0x1120
	ds_read_b64 v[234:235], v248 offset:0x1130
	s_waitcnt lgkmcnt(4)
	v_mfma_f32_32x32x16_bf16 v[18:33], v[236:239], v[244:247], v[18:33]
	ds_read_b64 v[236:237], v248 offset:0x2220
	ds_read_b64 v[238:239], v248 offset:0x2230
	v_mfma_f32_32x32x16_bf16 v[2:17], v[240:243], v[244:247], v[2:17]
	ds_read_b64 v[240:241], v248 offset:0x3320
	ds_read_b64 v[242:243], v248 offset:0x3330
	s_waitcnt lgkmcnt(4)
	v_cvt_pk_bf16_f32 v244, v74, v75
	v_cvt_pk_bf16_f32 v245, v76, v77
	v_cvt_pk_bf16_f32 v246, v78, v79
	v_cvt_pk_bf16_f32 v247, v80, v81
	s_nop 1
	v_mfma_f32_32x32x16_bf16 v[50:65], v[228:231], v[244:247], v[50:65]
	ds_read_b64 v[228:229], v248 offset:64
	ds_read_b64 v[230:231], v248 offset:0x50
	v_mfma_f32_32x32x16_bf16 v[34:49], v[232:235], v[244:247], v[34:49]
	ds_read_b64 v[232:233], v248 offset:0x1140
	ds_read_b64 v[234:235], v248 offset:0x1150
	s_waitcnt lgkmcnt(4)
	v_mfma_f32_32x32x16_bf16 v[18:33], v[236:239], v[244:247], v[18:33]
	ds_read_b64 v[236:237], v248 offset:0x2240
	ds_read_b64 v[238:239], v248 offset:0x2250
	v_mfma_f32_32x32x16_bf16 v[2:17], v[240:243], v[244:247], v[2:17]
	ds_read_b64 v[240:241], v248 offset:0x3340
	ds_read_b64 v[242:243], v248 offset:0x3350
	s_waitcnt lgkmcnt(4)
	v_cvt_pk_bf16_f32 v244, v82, v83
	v_cvt_pk_bf16_f32 v245, v84, v85
	v_cvt_pk_bf16_f32 v246, v86, v87
	v_cvt_pk_bf16_f32 v247, v88, v89
	s_nop 1
	v_mfma_f32_32x32x16_bf16 v[50:65], v[228:231], v[244:247], v[50:65]
	ds_read_b64 v[228:229], v248 offset:0x60
	ds_read_b64 v[230:231], v248 offset:0x70
	v_mfma_f32_32x32x16_bf16 v[34:49], v[232:235], v[244:247], v[34:49]
	ds_read_b64 v[232:233], v248 offset:0x1160
	ds_read_b64 v[234:235], v248 offset:0x1170
	s_waitcnt lgkmcnt(4)
	v_mfma_f32_32x32x16_bf16 v[18:33], v[236:239], v[244:247], v[18:33]
	ds_read_b64 v[236:237], v248 offset:0x2260
	ds_read_b64 v[238:239], v248 offset:0x2270
	v_mfma_f32_32x32x16_bf16 v[2:17], v[240:243], v[244:247], v[2:17]
	ds_read_b64 v[240:241], v248 offset:0x3360
	ds_read_b64 v[242:243], v248 offset:0x3370
	s_waitcnt lgkmcnt(4)
	v_cvt_pk_bf16_f32 v244, v90, v91
	v_cvt_pk_bf16_f32 v245, v92, v93
	v_cvt_pk_bf16_f32 v246, v94, v95
	v_cvt_pk_bf16_f32 v247, v96, v97
	s_nop 1
	v_mfma_f32_32x32x16_bf16 v[50:65], v[228:231], v[244:247], v[50:65]
	v_mfma_f32_32x32x16_bf16 v[34:49], v[232:235], v[244:247], v[34:49]
	s_waitcnt lgkmcnt(0)
	v_mfma_f32_32x32x16_bf16 v[18:33], v[236:239], v[244:247], v[18:33]
	v_mfma_f32_32x32x16_bf16 v[2:17], v[240:243], v[244:247], v[2:17]
	s_andn2_b64 vcc, exec, s[10:11]
	s_cbranch_vccnz .LBB0_827
	s_bitcmp1_b32 s18, 0
	s_cselect_b32 s6, 0xa800, 0
	v_add3_u32 v228, s6, v167, v169
	v_add3_u32 v229, s6, v199, v217
	v_add3_u32 v230, s6, v220, v221
	s_waitcnt vmcnt(2)
	ds_write_b128 v228, v[146:149]
	s_waitcnt vmcnt(1)
	ds_write_b128 v229, v[154:157]
	s_waitcnt vmcnt(0)
	ds_write_b128 v230, v[162:165]

; template <int DQK, int MODE, bool PIPE>
; DI void attn_core(const u16* __restrict__ Qg, const u16* __restrict__ Kg, const u16* __restrict__ Vtg, int ntiles,
;                   int kr_lo, int rs, int r_q, int c_q, int cs, const float* biasL, char* lds, f32x16 (&o)[4], float& l_out, int tid) {
;     ...
;   bf16x8 qf[NKS];
;   {
;     const u16* qrow = Qg + (size_t)(wid * 32 + r32) * DQK + h * 8;
; #pragma unroll
;     for (int ks = 0; ks < NKS; ++ks) qf[ks] = *(const bf16x8*)(qrow + ks * 16);
;   }
; #pragma unroll
;   for (int d = 0; d < 4; ++d)
; #pragma unroll
;     for (int i = 0; i < 16; ++i) o[d][i] = 0.f;
;   float m = 0.f, l = 0.f;
;   constexpr bool NEGM = (MODE == 0 && DQK == 64);
;   f32x16 negm;
; #pragma unroll
;   for (int i = 0; i < 16; ++i) negm[i] = 0.f;
;   u32x4 rk[KPT], rv[2];
;   auto keystart = [&](int t) -> int { if (MODE == 1 && t >= 4) return NCTX + 64 * (kr_lo + t - 4); return 64 * t; };
;   auto gloadK = [&](int t) {
;     const u16* kp = Kg + (size_t)keystart(t) * DQK;
; #pragma unroll
;     for (int j = 0; j < KPT; ++j) rk[j] = *(const u32x4*)(kp + (size_t)(tid + NT_ * j) * 8);
;   };
;   auto gloadV = [&](int t) {
;     const int key0 = keystart(t);
; #pragma unroll
;     for (int j = 0; j < 2; ++j) { const int q = tid + NT_ * j; rv[j] = *(const u32x4*)(Vtg + (size_t)(q >> 3) * NR + key0 + (q & 7) * 8); }
;   };
;   auto swriteK = [&](int b) {
;     char* base = lds + b * A_BUF;
; #pragma unroll
;     for (int j = 0; j < KPT; ++j) { const int q = tid + NT_ * j; const int row = q / NKP, pcs = q - row * NKP;
;       *(u32x4*)(base + row * KSTR + pcs * 16) = rk[j]; }
;   };
;   auto swriteV = [&](int b) {
;     char* base = lds + b * A_BUF;
; #pragma unroll
;     for (int j = 0; j < 2; ++j) { const int q = tid + NT_ * j; char* d = base + A_VOFF + (q >> 3) * 136 + (q & 7) * 16;
;       u32x2 lo = {rv[j][0], rv[j][1]}, hi = {rv[j][2], rv[j][3]};
;       *(u32x2*)d = lo; *(u32x2*)(d + 8) = hi; }
;   };
;   auto is_active = [&](int t) -> bool {
;     if (MODE == 1 && t >= 4) { const int kr = kr_lo + t - 4; return (kr >= rs) && (kr < rs + 8); }
;     return true;
;   };
;   auto qk = [&](int t, f32x16& p0, f32x16& p1) {
;     const char* kb = lds + (t & 1) * A_BUF + r32 * KSTR + h * 16;
;     if (MODE != 0) {
; #pragma unroll
;       for (int i = 0; i < 16; ++i) { p0[i] = 0.f; p1[i] = 0.f; }
;     }
;     if (MODE == 0) {
.LBB0_833:
	s_andn2_b64 vcc, exec, s[0:1]
	s_cbranch_vccnz .LBB0_699
	s_mul_hi_i32 s0, s67, 0x7e07e07f
	s_lshr_b32 s1, s0, 31
	s_ashr_i32 s8, s0, 5
	s_add_i32 s8, s8, s1
	s_mul_i32 s0, s8, 0x41
	s_sub_i32 s10, s67, s0
	v_readlane_b32 s16, v252, 6
	s_lshl_b32 s9, s10, 8
	s_mul_i32 s0, s8, 0x410000
	v_readlane_b32 s22, v252, 12
	s_mul_hi_i32 s1, s8, 0x410000
	v_readlane_b32 s23, v252, 13
	s_add_u32 s14, s22, s0
	s_addc_u32 s15, s23, s1
	s_lshl_b32 s12, s8, 1
	s_mul_i32 s6, s8, 0x8200
	s_ashr_i32 s11, s9, 31
	s_mul_hi_i32 s7, s12, 0x4100
	s_add_u32 s6, s6, s9
	s_addc_u32 s7, s7, s11
	v_readlane_b32 s18, v252, 8
	s_lshl_b64 s[6:7], s[6:7], 7
	v_readlane_b32 s17, v252, 7
	v_readlane_b32 s19, v252, 9
	s_add_u32 s16, s18, s6
	v_readlane_b32 s20, v252, 10
	s_addc_u32 s17, s19, s7
	s_add_u32 s18, s20, s0
	v_ashrrev_i32_e32 v0, 1, v216
	s_movk_i32 s20, 0xffe0
	v_and_or_b32 v2, v0, s20, v193
	v_ashrrev_i32_e32 v3, 31, v2
	v_lshlrev_b64 v[152:153], 7, v[2:3]
	v_lshl_add_u64 v[2:3], s[16:17], 0, v[152:153]
	v_lshlrev_b32_e32 v0, 4, v195
	v_lshl_add_u64 v[2:3], v[2:3], 0, v[0:1]
	global_load_dwordx4 v[114:117], v[2:3], off
	global_load_dwordx4 v[118:121], v[2:3], off offset:32
	global_load_dwordx4 v[122:125], v[2:3], off offset:64
	global_load_dwordx4 v[126:129], v[2:3], off offset:96
	v_ashrrev_i32_e32 v3, 3, v216
	v_mov_b64_e32 v[14:15], s[14:15]
	s_mov_b32 s16, 0x8200
	v_lshlrev_b32_e32 v2, 4, v216
	v_mad_i64_i32 v[4:5], s[14:15], v3, s16, v[14:15]
	v_and_b32_e32 v142, 0x70, v2
	v_mov_b32_e32 v143, v1
	v_readlane_b32 s21, v252, 11
	s_mul_hi_i32 s7, s12, 0x208000
	v_ashrrev_i32_e32 v217, 31, v216
	v_lshl_add_u64 v[154:155], v[4:5], 0, v[142:143]
	v_add_u32_e32 v4, 0x200, v216
	s_addc_u32 s19, s21, s7
	v_lshlrev_b64 v[158:159], 4, v[216:217]
	v_ashrrev_i32_e32 v4, 3, v4
	s_waitcnt vmcnt(4)
	v_lshl_add_u64 v[86:87], s[18:19], 0, v[158:159]
	v_mad_i64_i32 v[14:15], s[14:15], v4, s16, v[14:15]
	global_load_dwordx4 v[6:9], v[86:87], off
	v_lshl_add_u64 v[156:157], v[14:15], 0, v[142:143]
	global_load_dwordx4 v[10:13], v[154:155], off
	global_load_dwordx4 v[14:17], v[156:157], off
	v_lshrrev_b32_e32 v5, 29, v217
	v_add_u32_e32 v5, v216, v5
	v_ashrrev_i32_e32 v5, 3, v5
	v_mul_lo_u32 v18, v5, s46
	v_lshlrev_b32_e32 v5, 7, v5
	s_movk_i32 s14, 0x88
	v_sub_u32_e32 v2, v2, v5
	v_mul_lo_u32 v164, v3, s14
	v_add3_u32 v143, 0, v18, v2
	v_add_u32_e32 v2, 0, v164
	v_mul_lo_u32 v165, v4, s14
	v_add3_u32 v170, v2, v142, s33
	v_add_u32_e32 v2, 0, v165
	s_movk_i32 s14, 0x2000
	v_add3_u32 v171, v2, v142, s33
	v_mad_u32_u24 v19, v193, s46, 0
	s_mov_b32 s6, s0
	v_add_u32_e32 v174, v19, v0
	s_waitcnt vmcnt(2)
	ds_write_b128 v143, v[6:9]
	v_add_co_u32_e32 v6, vcc, s14, v86
	s_waitcnt vmcnt(1)
	ds_write2_b64 v170, v[10:11], v[12:13] offset1:1
	s_waitcnt vmcnt(0)
	ds_write2_b64 v171, v[14:15], v[16:17] offset1:1
	v_addc_co_u32_e32 v7, vcc, 0, v87, vcc
	global_load_dwordx4 v[82:85], v[6:7], off
	s_nop 0
	global_load_dwordx4 v[6:9], v[154:155], off offset:128
	global_load_dwordx4 v[10:13], v[156:157], off offset:128
	v_readlane_b32 s14, v254, 58
	s_waitcnt lgkmcnt(0)
	s_barrier
	v_add_u32_e32 v2, s14, v165
	v_add_u32_e32 v172, v2, v142
	v_add_u32_e32 v2, s14, v164
	v_add_u32_e32 v173, v2, v142
	s_waitcnt vmcnt(1)
	ds_write2_b64 v173, v[6:7], v[8:9] offset1:1
	s_waitcnt vmcnt(0)
	ds_write2_b64 v172, v[10:11], v[12:13] offset1:1
	global_load_dwordx4 v[130:133], v[154:155], off offset:256
	global_load_dwordx4 v[134:137], v[156:157], off offset:256
	ds_read_b128 v[6:9], v174 offset:0
	ds_read_b128 v[10:13], v174 offset:0x1200
	ds_read_b128 v[14:17], v174 offset:32
	ds_read_b128 v[52:55], v174 offset:0x1220
	s_waitcnt lgkmcnt(3)
	v_mfma_f32_32x32x16_bf16 v[20:35], v[6:9], v[114:117], 0
	ds_read_b128 v[6:9], v174 offset:64
	s_waitcnt lgkmcnt(3)
	v_mfma_f32_32x32x16_bf16 v[36:51], v[10:13], v[114:117], 0
	ds_read_b128 v[10:13], v174 offset:0x1240
	s_waitcnt lgkmcnt(3)
	v_mfma_f32_32x32x16_bf16 v[20:35], v[14:17], v[118:121], v[20:35]
	ds_read_b128 v[14:17], v174 offset:0x60
	s_waitcnt lgkmcnt(3)
	v_mfma_f32_32x32x16_bf16 v[36:51], v[52:55], v[118:121], v[36:51]
	ds_read_b128 v[52:55], v174 offset:0x1260
	s_waitcnt lgkmcnt(3)
	v_mfma_f32_32x32x16_bf16 v[20:35], v[6:9], v[122:125], v[20:35]
	s_waitcnt lgkmcnt(2)
	v_mfma_f32_32x32x16_bf16 v[36:51], v[10:13], v[122:125], v[36:51]
	s_waitcnt lgkmcnt(1)
	v_mfma_f32_32x32x16_bf16 v[20:35], v[14:17], v[126:129], v[20:35]
	s_waitcnt lgkmcnt(0)
	v_mfma_f32_32x32x16_bf16 v[36:51], v[52:55], v[126:129], v[36:51]
	v_max3_f32 v2, v20, v21, v22
	s_nop 7
	s_nop 7
	s_nop 7
	v_max3_f32 v5, v36, v37, v38
	v_max3_f32 v6, v23, v24, v25
	v_max3_f32 v7, v39, v40, v41
	v_max3_f32 v8, v26, v27, v28
	s_nop 0
	v_max3_f32 v2, v35, v51, v2
	v_max3_f32 v9, v42, v43, v44
	v_max3_f32 v10, v29, v30, v31
	v_max3_f32 v11, v45, v46, v47
	v_max3_f32 v5, v5, v6, v7
	v_max3_f32 v12, v32, v33, v34
	v_max3_f32 v13, v48, v49, v50
	s_nop 0
	v_max3_f32 v6, v8, v9, v10
	v_max3_f32 v7, v11, v12, v13
	s_nop 0
	v_max3_f32 v2, v2, v5, v6
	s_nop 0
	v_max_f32 v2, v7, v2
	s_nop 0
	v_cmp_gt_f32_e64 vcc, |v2|, s66
	s_cbranch_vccz .LBB0_836
	v_and_b32_e32 v6, 64, v189
	v_xor_b32_e32 v5, 32, v189
	v_add_u32_e32 v6, 64, v6
	v_cmp_lt_i32_e32 vcc, v5, v6
	s_nop 1
	v_cndmask_b32_e32 v5, v189, v5, vcc
	v_lshlrev_b32_e32 v5, 2, v5
	ds_bpermute_b32 v5, v5, v2
	v_max_f32_e32 v2, v2, v2
	s_waitcnt lgkmcnt(0)
	v_max_f32_e32 v5, v5, v5
	v_max_f32_e32 v6, v2, v5
	v_max_f32_e32 v2, 0, v6
	v_exp_f32_e64 v2, -v2
	v_add_f32_e32 v175, 0, v6
	v_pk_add_f32 v[20:21], v[20:21], v[6:7] op_sel_hi:[1,0] neg_lo:[0,1] neg_hi:[0,1]
	v_pk_add_f32 v[36:37], v[36:37], v[6:7] op_sel_hi:[1,0] neg_lo:[0,1] neg_hi:[0,1]
	v_pk_add_f32 v[22:23], v[22:23], v[6:7] op_sel_hi:[1,0] neg_lo:[0,1] neg_hi:[0,1]
	v_mul_f32_e32 v2, 0, v2
	v_pk_add_f32 v[38:39], v[38:39], v[6:7] op_sel_hi:[1,0] neg_lo:[0,1] neg_hi:[0,1]
	v_pk_add_f32 v[24:25], v[24:25], v[6:7] op_sel_hi:[1,0] neg_lo:[0,1] neg_hi:[0,1]
	v_pk_add_f32 v[40:41], v[40:41], v[6:7] op_sel_hi:[1,0] neg_lo:[0,1] neg_hi:[0,1]
	v_pk_add_f32 v[26:27], v[26:27], v[6:7] op_sel_hi:[1,0] neg_lo:[0,1] neg_hi:[0,1]
	v_pk_add_f32 v[42:43], v[42:43], v[6:7] op_sel_hi:[1,0] neg_lo:[0,1] neg_hi:[0,1]
	v_pk_add_f32 v[28:29], v[28:29], v[6:7] op_sel_hi:[1,0] neg_lo:[0,1] neg_hi:[0,1]
	v_pk_add_f32 v[44:45], v[44:45], v[6:7] op_sel_hi:[1,0] neg_lo:[0,1] neg_hi:[0,1]
	v_pk_add_f32 v[30:31], v[30:31], v[6:7] op_sel_hi:[1,0] neg_lo:[0,1] neg_hi:[0,1]
	v_pk_add_f32 v[46:47], v[46:47], v[6:7] op_sel_hi:[1,0] neg_lo:[0,1] neg_hi:[0,1]
	v_pk_add_f32 v[32:33], v[32:33], v[6:7] op_sel_hi:[1,0] neg_lo:[0,1] neg_hi:[0,1]
	v_pk_add_f32 v[48:49], v[48:49], v[6:7] op_sel_hi:[1,0] neg_lo:[0,1] neg_hi:[0,1]
	v_pk_add_f32 v[34:35], v[34:35], v[6:7] op_sel_hi:[1,0] neg_lo:[0,1] neg_hi:[0,1]
	v_pk_add_f32 v[50:51], v[50:51], v[6:7] op_sel_hi:[1,0] neg_lo:[0,1] neg_hi:[0,1]
	v_xor_b32_e32 v18, 0x80000000, v175
	s_branch .LBB0_837

; #define MFMA(a, b, c) __builtin_amdgcn_mfma_f32_32x32x16_bf16((a), (b), (c), 0, 0, 0)
; template <int N> DI void lgkm_wait() { asm volatile("s_waitcnt lgkmcnt(%0)" :: "i"(N) : "memory"); }
; #define SBAR() __builtin_amdgcn_sched_barrier(0)
;   static DI void run(unsigned vaddr, s16x4 (&lo)[R], s16x4 (&hi)[R], const f32x16& p0, const f32x16& p1, bf16x8& pfc, f32x16 (&o)[4]) {
;     constexpr int issued = (J + R < NF) ? (J + R) : NF;
;     if constexpr ((J & 3) == 0) {
;       if constexpr ((J >> 2) == 0) pfc = pack8<0>(p0);
;       else if constexpr ((J >> 2) == 1) pfc = pack8<8>(p0);
;       else if constexpr ((J >> 2) == 2) pfc = pack8<0>(p1);
;       else pfc = pack8<8>(p1);
;     }
;     lgkm_wait<2 * (issued - J - 1)>(); SBAR();
;     o[J & 3] = MFMA(__builtin_shufflevector(lo[J % R], hi[J % R], 0, 1, 2, 3, 4, 5, 6, 7), pfc, o[J & 3]);
;     SBAR();
;     if (J + R < NF) {
;       constexpr int off = ((J + R) & 3) * 32 * 136 + ((J + R) >> 2) * 32;
;       lo[J % R] = lds_rd64<off>(vaddr); hi[J % R] = lds_rd64<off + 16>(vaddr); SBAR();
;     }
;     if constexpr (J + 1 < NF) PvStep<J + 1, NF, R>::run(vaddr, lo, hi, p0, p1, pfc, o);
;   }
; template <int DQK, int MODE, bool PIPE>
; DI void attn_core(const u16* __restrict__ Qg, const u16* __restrict__ Kg, const u16* __restrict__ Vtg, int ntiles,
;                   int kr_lo, int rs, int r_q, int c_q, int cs, const float* biasL, char* lds, f32x16 (&o)[4], float& l_out, int tid) {
;     ...
;     for (int i = 0; i < 16; ++i) { p0[i] = __builtin_amdgcn_exp2f(p0[i]); p1[i] = __builtin_amdgcn_exp2f(p1[i]); ps += p0[i] + p1[i]; }
;     l += ps;
;     const char* vb = lds + (t & 1) * A_BUF + A_VOFF + r32 * 136 + h * 8;
;     {
;       bf16x8 pfc;
;       constexpr int R = PV_RING;
;       const unsigned vaddr = (unsigned)(size_t)vb;
;       s16x4 vlo[R], vhi[R];
;       SBAR();
;       vlo[0] = lds_rd64<0>(vaddr); vhi[0] = lds_rd64<16>(vaddr);
;       vlo[1] = lds_rd64<32 * 136>(vaddr); vhi[1] = lds_rd64<32 * 136 + 16>(vaddr);
;       if (R > 2) { vlo[2 % R] = lds_rd64<64 * 136>(vaddr); vhi[2 % R] = lds_rd64<64 * 136 + 16>(vaddr); }
;       if (R > 3) { vlo[3 % R] = lds_rd64<96 * 136>(vaddr); vhi[3 % R] = lds_rd64<96 * 136 + 16>(vaddr); }
;       SBAR();
;       __builtin_amdgcn_s_setprio(1);
;       PvStep<0, 16, R>::run(vaddr, vlo, vhi, p0, p1, pfc, o);
;       __builtin_amdgcn_s_setprio(0);
.LBB0_837:
	v_exp_f32_e32 v52, v20
	v_exp_f32_e32 v146, v36
	v_exp_f32_e32 v53, v21
	v_exp_f32_e32 v147, v37
	v_exp_f32_e32 v54, v22
	v_exp_f32_e32 v148, v38
	v_exp_f32_e32 v55, v23
	v_exp_f32_e32 v149, v39
	v_add_f32_e32 v20, v146, v52
	v_add_f32_e32 v20, 0, v20
	v_add_f32_e32 v21, v147, v53
	v_add_f32_e32 v20, v21, v20
	v_add_f32_e32 v21, v148, v54
	v_add_f32_e32 v20, v21, v20
	v_add_f32_e32 v21, v149, v55
	v_add_f32_e32 v36, v21, v20
	v_exp_f32_e32 v21, v24
	v_exp_f32_e32 v23, v40
	v_exp_f32_e32 v20, v25
	v_exp_f32_e32 v22, v41
	v_lshlrev_b32_e32 v166, 3, v195
	s_cmp_eq_u32 s10, 0
	v_mad_i64_i32 v[90:91], s[14:15], v3, s16, 0
	v_pk_add_f32 v[24:25], v[22:23], v[20:21]
	s_mov_b32 s53, 0x8200
	v_add_f32_e32 v25, v25, v36
	v_pk_mov_b32 v[36:37], v[20:21], v[20:21] op_sel:[1,0]
	v_pk_mov_b32 v[20:21], v[22:23], v[22:23] op_sel:[1,0]
	v_add_f32_e32 v38, v24, v25
	v_exp_f32_e32 v23, v26
	v_exp_f32_e32 v25, v42
	v_exp_f32_e32 v22, v27
	v_exp_f32_e32 v24, v43
	v_mad_i64_i32 v[88:89], s[14:15], v4, s16, 0
	v_mul_u32_u24_e32 v167, 0x90, v193
	v_pk_add_f32 v[26:27], v[24:25], v[22:23]
	s_cselect_b32 s10, 4, 0x104
	v_add_f32_e32 v27, v27, v38
	v_pk_mov_b32 v[38:39], v[22:23], v[22:23] op_sel:[1,0]
	v_add_f32_e32 v40, v26, v27
	v_exp_f32_e32 v23, v28
	v_exp_f32_e32 v27, v44
	v_exp_f32_e32 v22, v29
	v_exp_f32_e32 v26, v45
	v_mul_u32_u24_e32 v168, 0x88, v193
	v_mov_b32_e32 v3, v2
	v_pk_mov_b32 v[108:109], v[22:23], v[22:23] op_sel:[1,0]
	v_pk_add_f32 v[28:29], v[26:27], v[22:23]
	v_pk_mov_b32 v[22:23], v[26:27], v[26:27] op_sel:[1,0]
	v_add_f32_e32 v29, v29, v40
	v_add_f32_e32 v40, v28, v29
	v_exp_f32_e32 v27, v30
	v_exp_f32_e32 v29, v46
	v_exp_f32_e32 v26, v31
	v_exp_f32_e32 v28, v47
	v_mov_b32_e32 v4, v2
	v_mov_b32_e32 v5, v2
	v_pk_mov_b32 v[110:111], v[26:27], v[26:27] op_sel:[1,0]
	v_pk_add_f32 v[30:31], v[28:29], v[26:27]
	v_pk_mov_b32 v[26:27], v[28:29], v[28:29] op_sel:[1,0]
	v_add_f32_e32 v31, v31, v40
	v_add_f32_e32 v40, v30, v31
	v_exp_f32_e32 v29, v32
	v_exp_f32_e32 v31, v48
	v_exp_f32_e32 v28, v33
	v_exp_f32_e32 v30, v49
	v_mov_b32_e32 v6, v2
	v_mov_b32_e32 v7, v2
	v_pk_mov_b32 v[112:113], v[28:29], v[28:29] op_sel:[1,0]
	v_pk_add_f32 v[32:33], v[30:31], v[28:29]
	v_pk_mov_b32 v[138:139], v[30:31], v[30:31] op_sel:[1,0]
	v_exp_f32_e32 v29, v34
	v_exp_f32_e32 v31, v50
	v_exp_f32_e32 v28, v35
	v_exp_f32_e32 v30, v51
	v_add_f32_e32 v33, v33, v40
	v_add_f32_e32 v40, v32, v33
	v_pk_mov_b32 v[140:141], v[28:29], v[28:29] op_sel:[1,0]
	v_pk_add_f32 v[32:33], v[30:31], v[28:29]
	v_mov_b32_e32 v8, v2
	v_add_f32_e32 v33, v33, v40
	v_add_f32_e32 v28, v32, v33
	v_add_f32_e32 v176, v2, v28
	v_lshlrev_b32_e32 v28, 3, v193
	v_sub_u32_e32 v19, v19, v28
	v_mov_b32_e32 v9, v2
	v_mov_b32_e32 v10, v2
	v_mov_b32_e32 v11, v2
	v_mov_b32_e32 v12, v2
	v_mov_b32_e32 v13, v2
	v_mov_b32_e32 v14, v2
	v_mov_b32_e32 v15, v2
	v_mov_b32_e32 v16, v2
	v_mov_b32_e32 v17, v2
	v_pk_mov_b32 v[24:25], v[24:25], v[24:25] op_sel:[1,0]
	v_pk_mov_b32 v[144:145], v[30:31], v[30:31] op_sel:[1,0]
	v_add3_u32 v169, v19, v166, s33
	ds_read_b64 v[28:29], v169 offset:0
	ds_read_b64 v[30:31], v169 offset:16
	ds_read_b64 v[32:33], v169 offset:0x1100
	ds_read_b64 v[34:35], v169 offset:0x1110
	ds_read_b64 v[92:93], v169 offset:0x2200
	ds_read_b64 v[94:95], v169 offset:0x2210
	ds_read_b64 v[96:97], v169 offset:0x3300
	ds_read_b64 v[98:99], v169 offset:0x3310
	s_waitcnt lgkmcnt(6)
	v_cvt_pk_bf16_f32 v100, v52, v53
	v_cvt_pk_bf16_f32 v101, v54, v55
	v_cvt_pk_bf16_f32 v102, v36, v37
	v_cvt_pk_bf16_f32 v103, v38, v39
	s_nop 1
	v_mfma_f32_32x32x16_bf16 v[66:81], v[28:31], v[100:103], v[2:17]
	ds_read_b64 v[28:29], v169 offset:32
	ds_read_b64 v[30:31], v169 offset:48
	s_waitcnt lgkmcnt(6)
	v_mfma_f32_32x32x16_bf16 v[50:65], v[32:35], v[100:103], v[2:17]
	ds_read_b64 v[104:105], v169 offset:0x1120
	ds_read_b64 v[106:107], v169 offset:0x1130
	s_waitcnt lgkmcnt(6)
; #define MFMA(a, b, c) __builtin_amdgcn_mfma_f32_32x32x16_bf16((a), (b), (c), 0, 0, 0)
; template <int N> DI void lgkm_wait() { asm volatile("s_waitcnt lgkmcnt(%0)" :: "i"(N) : "memory"); }
; #define SBAR() __builtin_amdgcn_sched_barrier(0)
;   static DI void run(unsigned vaddr, s16x4 (&lo)[R], s16x4 (&hi)[R], const f32x16& p0, const f32x16& p1, bf16x8& pfc, f32x16 (&o)[4]) {
;     constexpr int issued = (J + R < NF) ? (J + R) : NF;
;     if constexpr ((J & 3) == 0) {
;       if constexpr ((J >> 2) == 0) pfc = pack8<0>(p0);
;       else if constexpr ((J >> 2) == 1) pfc = pack8<8>(p0);
;       else if constexpr ((J >> 2) == 2) pfc = pack8<0>(p1);
;       else pfc = pack8<8>(p1);
;     }
;     lgkm_wait<2 * (issued - J - 1)>(); SBAR();
;     o[J & 3] = MFMA(__builtin_shufflevector(lo[J % R], hi[J % R], 0, 1, 2, 3, 4, 5, 6, 7), pfc, o[J & 3]);
;     SBAR();
;     if (J + R < NF) {
;       constexpr int off = ((J + R) & 3) * 32 * 136 + ((J + R) >> 2) * 32;
;       lo[J % R] = lds_rd64<off>(vaddr); hi[J % R] = lds_rd64<off + 16>(vaddr); SBAR();
;     }
;     if constexpr (J + 1 < NF) PvStep<J + 1, NF, R>::run(vaddr, lo, hi, p0, p1, pfc, o);
;   }
; template <int DQK, int MODE, bool PIPE>
; DI void attn_core(const u16* __restrict__ Qg, const u16* __restrict__ Kg, const u16* __restrict__ Vtg, int ntiles,
;                   int kr_lo, int rs, int r_q, int c_q, int cs, const float* biasL, char* lds, f32x16 (&o)[4], float& l_out, int tid) {
;     ...
;       if (t + 2 < ntiles) swriteK(t & 1);
;       if (t + 3 < ntiles) gloadK(t + 3);
;     } else {
;       if (is_active(t)) { qk(t, c0, c1); sm_pv(t, c0, c1); }
;       if (t + 1 < ntiles) swriteK((t + 1) & 1);
;       if (t + 2 < ntiles) gloadK(t + 2);
;     }
;     __syncthreads();
	v_mfma_f32_32x32x16_bf16 v[34:49], v[92:95], v[100:103], v[2:17]
	ds_read_b64 v[92:93], v169 offset:0x2220
	ds_read_b64 v[94:95], v169 offset:0x2230
	s_waitcnt lgkmcnt(6)
	v_mfma_f32_32x32x16_bf16 v[2:17], v[96:99], v[100:103], v[2:17]
	ds_read_b64 v[96:97], v169 offset:0x3320
	ds_read_b64 v[98:99], v169 offset:0x3330
	s_waitcnt lgkmcnt(6)
	v_cvt_pk_bf16_f32 v100, v108, v109
	v_cvt_pk_bf16_f32 v101, v110, v111
	v_cvt_pk_bf16_f32 v102, v112, v113
	v_cvt_pk_bf16_f32 v103, v140, v141
	s_nop 1
	v_mfma_f32_32x32x16_bf16 v[66:81], v[28:31], v[100:103], v[66:81]
	ds_read_b64 v[28:29], v169 offset:64
	ds_read_b64 v[30:31], v169 offset:0x50
	s_waitcnt lgkmcnt(6)
	v_mfma_f32_32x32x16_bf16 v[50:65], v[104:107], v[100:103], v[50:65]
	ds_read_b64 v[104:105], v169 offset:0x1140
	ds_read_b64 v[106:107], v169 offset:0x1150
	s_waitcnt lgkmcnt(6)
	v_mfma_f32_32x32x16_bf16 v[34:49], v[92:95], v[100:103], v[34:49]
	ds_read_b64 v[92:93], v169 offset:0x2240
	ds_read_b64 v[94:95], v169 offset:0x2250
	s_waitcnt lgkmcnt(6)
	v_mfma_f32_32x32x16_bf16 v[2:17], v[96:99], v[100:103], v[2:17]
	ds_read_b64 v[96:97], v169 offset:0x3340
	ds_read_b64 v[98:99], v169 offset:0x3350
	s_waitcnt lgkmcnt(6)
	v_cvt_pk_bf16_f32 v100, v146, v147
	v_cvt_pk_bf16_f32 v101, v148, v149
	v_cvt_pk_bf16_f32 v102, v20, v21
	v_cvt_pk_bf16_f32 v103, v24, v25
	s_nop 1
	v_mfma_f32_32x32x16_bf16 v[66:81], v[28:31], v[100:103], v[66:81]
	ds_read_b64 v[28:29], v169 offset:0x60
	ds_read_b64 v[30:31], v169 offset:0x70
	s_waitcnt lgkmcnt(6)
	v_mfma_f32_32x32x16_bf16 v[50:65], v[104:107], v[100:103], v[50:65]
	ds_read_b64 v[104:105], v169 offset:0x1160
	ds_read_b64 v[106:107], v169 offset:0x1170
	s_waitcnt lgkmcnt(6)
	v_mfma_f32_32x32x16_bf16 v[34:49], v[92:95], v[100:103], v[34:49]
	ds_read_b64 v[92:93], v169 offset:0x2260
	ds_read_b64 v[94:95], v169 offset:0x2270
	s_waitcnt lgkmcnt(6)
	v_mfma_f32_32x32x16_bf16 v[2:17], v[96:99], v[100:103], v[2:17]
	ds_read_b64 v[96:97], v169 offset:0x3360
	ds_read_b64 v[98:99], v169 offset:0x3370
	s_waitcnt lgkmcnt(6)
	v_cvt_pk_bf16_f32 v20, v22, v23
	v_cvt_pk_bf16_f32 v21, v26, v27
	v_cvt_pk_bf16_f32 v22, v138, v139
	v_cvt_pk_bf16_f32 v23, v144, v145
	s_nop 1
	v_mfma_f32_32x32x16_bf16 v[66:81], v[28:31], v[20:23], v[66:81]
	s_waitcnt lgkmcnt(4)
	v_mfma_f32_32x32x16_bf16 v[50:65], v[104:107], v[20:23], v[50:65]
	s_waitcnt lgkmcnt(2)
	v_mfma_f32_32x32x16_bf16 v[34:49], v[92:95], v[20:23], v[34:49]
	s_waitcnt lgkmcnt(0)
	v_mfma_f32_32x32x16_bf16 v[2:17], v[96:99], v[20:23], v[2:17]
	s_movk_i32 s14, 0x4000
	v_add_co_u32_e32 v20, vcc, s14, v86
	v_lshl_add_u64 v[160:161], s[6:7], 0, v[158:159]
	s_nop 0
	v_addc_co_u32_e32 v21, vcc, 0, v87, vcc
	global_load_dwordx4 v[138:141], v[20:21], off
	v_readlane_b32 s6, v254, 32
	v_readlane_b32 s7, v254, 33
	v_and_b32_e32 v19, 7, v216
	v_lshl_add_u64 v[20:21], s[0:1], 0, v[90:91]
	v_lshl_add_u64 v[144:145], s[6:7], 0, v[160:161]
	v_lshlrev_b32_e32 v22, 4, v19
	v_mov_b32_e32 v23, v1
	v_readlane_b32 s6, v254, 34
	v_lshl_add_u64 v[20:21], v[20:21], 0, v[22:23]
	v_readlane_b32 s7, v254, 35
	s_mov_b32 s15, 1
	v_mov_b32_e32 v19, v18
	v_lshl_add_u64 v[146:147], s[6:7], 0, v[20:21]
	v_lshl_add_u64 v[20:21], s[0:1], 0, v[88:89]
	v_lshl_add_u64 v[20:21], v[20:21], 0, v[22:23]
	v_lshl_add_u64 v[148:149], s[6:7], 0, v[20:21]
	v_mov_b64_e32 v[150:151], v[148:149]
	v_mov_b64_e32 v[162:163], v[146:147]
	v_mov_b32_e32 v20, v18
	v_mov_b32_e32 v21, v18
	v_mov_b32_e32 v22, v18
	v_mov_b32_e32 v23, v18
	v_mov_b32_e32 v24, v18
	v_mov_b32_e32 v25, v18
	v_mov_b32_e32 v26, v18
	v_mov_b32_e32 v27, v18
	v_mov_b32_e32 v28, v18
	v_mov_b32_e32 v29, v18
	v_mov_b32_e32 v30, v18
	v_mov_b32_e32 v31, v18
	v_mov_b32_e32 v32, v18
	v_mov_b32_e32 v33, v18
	ds_write_b128 v143, v[82:85] offset:43008
	s_waitcnt lgkmcnt(0)
	s_barrier

; template <int DQK, int MODE, bool PIPE>
; DI void attn_core(const u16* __restrict__ Qg, const u16* __restrict__ Kg, const u16* __restrict__ Vtg, int ntiles,
;                   int kr_lo, int rs, int r_q, int c_q, int cs, const float* biasL, char* lds, f32x16 (&o)[4], float& l_out, int tid) {
;     ...
;   auto qk = [&](int t, f32x16& p0, f32x16& p1) {
;     const char* kb = lds + (t & 1) * A_BUF + r32 * KSTR + h * 16;
;     if (MODE != 0) {
; #pragma unroll
;       for (int i = 0; i < 16; ++i) { p0[i] = 0.f; p1[i] = 0.f; }
;     }
;     if (MODE == 0) {
;       constexpr int R = 4, NF = 2 * NKS;
;       const unsigned kaddr = (unsigned)(size_t)kb;
;       bf16x8 f[R];
;       SBAR();
;       f[0] = lds_rd128<0>(kaddr); f[1] = lds_rd128<32 * KSTR>(kaddr); f[2] = lds_rd128<32>(kaddr); f[3] = lds_rd128<32 * KSTR + 32>(kaddr);
;       SBAR();
;       __builtin_amdgcn_s_setprio(1);
;       QkStep<DQK, 0, NF, R>::run(kaddr, f, qf, p0, p1, negm);
;       __builtin_amdgcn_s_setprio(0);
;     ...
;     float tmx;
;     {
;       float u[11];
; #pragma unroll
;       for (int i = 0; i < 5; ++i) {
;         asm("v_max3_f32 %0, %1, %2, %3" : "=v"(u[2 * i]) : "v"(p0[3 * i]), "v"(p0[3 * i + 1]), "v"(p0[3 * i + 2]));
;         asm("v_max3_f32 %0, %1, %2, %3" : "=v"(u[2 * i + 1]) : "v"(p1[3 * i]), "v"(p1[3 * i + 1]), "v"(p1[3 * i + 2]));
;       }
;       asm("v_max3_f32 %0, %1, %2, %3" : "=v"(u[10]) : "v"(p0[15]), "v"(p1[15]), "v"(u[0]));
;       float w0, w1, w2, w3;
;       asm("v_max3_f32 %0, %1, %2, %3" : "=v"(w0) : "v"(u[1]), "v"(u[2]), "v"(u[3]));
;       asm("v_max3_f32 %0, %1, %2, %3" : "=v"(w1) : "v"(u[4]), "v"(u[5]), "v"(u[6]));
;       asm("v_max3_f32 %0, %1, %2, %3" : "=v"(w2) : "v"(u[7]), "v"(u[8]), "v"(u[9]));
;       asm("v_max3_f32 %0, %1, %2, %3" : "=v"(w3) : "v"(u[10]), "v"(w0), "v"(w1));
;       asm("v_max_f32 %0, %1, %2" : "=v"(tmx) : "v"(w2), "v"(w3));
;     }
;     const bool t0 = (t == 0);
;     if (__any(tmx > THR || (t0 && tmx < -THR))) {
;       tmx = fmaxf(tmx, __shfl_xor(tmx, 32));
;       const float delta = t0 ? tmx : fmaxf(tmx, 0.f);
;       const float alpha = __builtin_amdgcn_exp2f(-fmaxf(delta, 0.f));
;       m += delta; l *= alpha;
; #pragma unroll
;       for (int d = 0; d < 4; ++d)
; #pragma unroll
;         for (int i = 0; i < 16; ++i) o[d][i] *= alpha;
; #pragma unroll
;       for (int i = 0; i < 16; ++i) { p0[i] -= delta; p1[i] -= delta; }
.LBB0_842:
	s_bitcmp1_b32 s15, 0
	s_cselect_b32 s15, 0xa800, 0
	v_add3_u32 v177, s15, v167, v0
	ds_read_b128 v[98:101], v177 offset:0
	ds_read_b128 v[216:219], v177 offset:0x1200
	ds_read_b128 v[220:223], v177 offset:32
	ds_read_b128 v[224:227], v177 offset:0x1220
	s_waitcnt lgkmcnt(2)
	v_mfma_f32_32x32x16_bf16 v[82:97], v[98:101], v[114:117], v[18:33]
	ds_read_b128 v[228:231], v177 offset:64
	v_mfma_f32_32x32x16_bf16 v[98:113], v[216:219], v[114:117], v[18:33]
	ds_read_b128 v[216:219], v177 offset:0x1240
	s_waitcnt lgkmcnt(2)
	v_mfma_f32_32x32x16_bf16 v[82:97], v[220:223], v[118:121], v[82:97]
	ds_read_b128 v[220:223], v177 offset:0x60
	v_mfma_f32_32x32x16_bf16 v[98:113], v[224:227], v[118:121], v[98:113]
	ds_read_b128 v[224:227], v177 offset:0x1260
	s_waitcnt lgkmcnt(2)
	v_mfma_f32_32x32x16_bf16 v[82:97], v[228:231], v[122:125], v[82:97]
	v_mfma_f32_32x32x16_bf16 v[98:113], v[216:219], v[122:125], v[98:113]
	s_waitcnt lgkmcnt(0)
	v_mfma_f32_32x32x16_bf16 v[82:97], v[220:223], v[126:129], v[82:97]
	v_mfma_f32_32x32x16_bf16 v[98:113], v[224:227], v[126:129], v[98:113]
	v_max3_f32 v177, v82, v83, v84
	s_nop 7
	s_nop 7
	v_max3_f32 v199, v98, v99, v100
	v_max3_f32 v216, v85, v86, v87
	v_max3_f32 v217, v101, v102, v103
	v_max3_f32 v218, v88, v89, v90
	v_max3_f32 v177, v97, v113, v177
	v_max3_f32 v219, v104, v105, v106
	v_max3_f32 v220, v91, v92, v93
	v_max3_f32 v221, v107, v108, v109
	v_max3_f32 v199, v199, v216, v217
	v_max3_f32 v222, v94, v95, v96
	v_max3_f32 v223, v110, v111, v112
	v_max3_f32 v216, v218, v219, v220
	v_max3_f32 v217, v221, v222, v223
	v_max3_f32 v177, v177, v199, v216
	v_max_f32 v177, v217, v177
	v_cmp_lt_f32_e32 vcc, s66, v177
	s_cbranch_vccz .LBB0_844
	v_and_b32_e32 v19, 64, v189
	v_xor_b32_e32 v18, 32, v189
	v_add_u32_e32 v19, 64, v19
	v_cmp_lt_i32_e32 vcc, v18, v19
	s_nop 1
	v_cndmask_b32_e32 v18, v189, v18, vcc
	v_lshlrev_b32_e32 v18, 2, v18
	ds_bpermute_b32 v18, v18, v177
	s_waitcnt lgkmcnt(0)
	v_max3_f32 v18, v177, v18, 0
	v_exp_f32_e64 v20, -v18
	v_add_f32_e32 v175, v175, v18
	v_pk_add_f32 v[82:83], v[82:83], v[18:19] op_sel_hi:[1,0] neg_lo:[0,1] neg_hi:[0,1]
	v_pk_add_f32 v[98:99], v[98:99], v[18:19] op_sel_hi:[1,0] neg_lo:[0,1] neg_hi:[0,1]
	v_pk_add_f32 v[84:85], v[84:85], v[18:19] op_sel_hi:[1,0] neg_lo:[0,1] neg_hi:[0,1]
	v_pk_add_f32 v[100:101], v[100:101], v[18:19] op_sel_hi:[1,0] neg_lo:[0,1] neg_hi:[0,1]
	v_pk_add_f32 v[86:87], v[86:87], v[18:19] op_sel_hi:[1,0] neg_lo:[0,1] neg_hi:[0,1]
	v_pk_add_f32 v[102:103], v[102:103], v[18:19] op_sel_hi:[1,0] neg_lo:[0,1] neg_hi:[0,1]
	v_pk_add_f32 v[88:89], v[88:89], v[18:19] op_sel_hi:[1,0] neg_lo:[0,1] neg_hi:[0,1]
	v_pk_add_f32 v[104:105], v[104:105], v[18:19] op_sel_hi:[1,0] neg_lo:[0,1] neg_hi:[0,1]
	v_pk_add_f32 v[90:91], v[90:91], v[18:19] op_sel_hi:[1,0] neg_lo:[0,1] neg_hi:[0,1]
	v_pk_add_f32 v[106:107], v[106:107], v[18:19] op_sel_hi:[1,0] neg_lo:[0,1] neg_hi:[0,1]
	v_pk_add_f32 v[92:93], v[92:93], v[18:19] op_sel_hi:[1,0] neg_lo:[0,1] neg_hi:[0,1]
	v_pk_add_f32 v[108:109], v[108:109], v[18:19] op_sel_hi:[1,0] neg_lo:[0,1] neg_hi:[0,1]
	v_pk_add_f32 v[94:95], v[94:95], v[18:19] op_sel_hi:[1,0] neg_lo:[0,1] neg_hi:[0,1]
	v_pk_add_f32 v[110:111], v[110:111], v[18:19] op_sel_hi:[1,0] neg_lo:[0,1] neg_hi:[0,1]
	v_pk_add_f32 v[96:97], v[96:97], v[18:19] op_sel_hi:[1,0] neg_lo:[0,1] neg_hi:[0,1]
	v_pk_add_f32 v[112:113], v[112:113], v[18:19] op_sel_hi:[1,0] neg_lo:[0,1] neg_hi:[0,1]
	v_xor_b32_e32 v18, 0x80000000, v175
	v_mul_f32_e32 v176, v176, v20
	v_pk_mul_f32 v[80:81], v[80:81], v[20:21] op_sel_hi:[1,0]
	v_pk_mul_f32 v[78:79], v[78:79], v[20:21] op_sel_hi:[1,0]
	v_pk_mul_f32 v[76:77], v[76:77], v[20:21] op_sel_hi:[1,0]
	v_pk_mul_f32 v[74:75], v[74:75], v[20:21] op_sel_hi:[1,0]
	v_pk_mul_f32 v[72:73], v[72:73], v[20:21] op_sel_hi:[1,0]
	v_pk_mul_f32 v[70:71], v[70:71], v[20:21] op_sel_hi:[1,0]
	v_pk_mul_f32 v[68:69], v[68:69], v[20:21] op_sel_hi:[1,0]
	v_pk_mul_f32 v[66:67], v[66:67], v[20:21] op_sel_hi:[1,0]
	v_pk_mul_f32 v[64:65], v[64:65], v[20:21] op_sel_hi:[1,0]
	v_pk_mul_f32 v[62:63], v[62:63], v[20:21] op_sel_hi:[1,0]
	v_pk_mul_f32 v[60:61], v[60:61], v[20:21] op_sel_hi:[1,0]
	v_pk_mul_f32 v[58:59], v[58:59], v[20:21] op_sel_hi:[1,0]
	v_pk_mul_f32 v[56:57], v[56:57], v[20:21] op_sel_hi:[1,0]
	v_pk_mul_f32 v[54:55], v[54:55], v[20:21] op_sel_hi:[1,0]
	v_pk_mul_f32 v[52:53], v[52:53], v[20:21] op_sel_hi:[1,0]
	v_pk_mul_f32 v[50:51], v[50:51], v[20:21] op_sel_hi:[1,0]
	v_pk_mul_f32 v[48:49], v[48:49], v[20:21] op_sel_hi:[1,0]
	v_pk_mul_f32 v[46:47], v[46:47], v[20:21] op_sel_hi:[1,0]
	v_pk_mul_f32 v[44:45], v[44:45], v[20:21] op_sel_hi:[1,0]
	v_pk_mul_f32 v[42:43], v[42:43], v[20:21] op_sel_hi:[1,0]
	v_pk_mul_f32 v[40:41], v[40:41], v[20:21] op_sel_hi:[1,0]
	v_pk_mul_f32 v[38:39], v[38:39], v[20:21] op_sel_hi:[1,0]
	v_pk_mul_f32 v[36:37], v[36:37], v[20:21] op_sel_hi:[1,0]
	v_pk_mul_f32 v[34:35], v[34:35], v[20:21] op_sel_hi:[1,0]
	v_pk_mul_f32 v[16:17], v[16:17], v[20:21] op_sel_hi:[1,0]
	v_pk_mul_f32 v[14:15], v[14:15], v[20:21] op_sel_hi:[1,0]
	v_pk_mul_f32 v[12:13], v[12:13], v[20:21] op_sel_hi:[1,0]
	v_pk_mul_f32 v[10:11], v[10:11], v[20:21] op_sel_hi:[1,0]
	v_pk_mul_f32 v[8:9], v[8:9], v[20:21] op_sel_hi:[1,0]
	v_pk_mul_f32 v[6:7], v[6:7], v[20:21] op_sel_hi:[1,0]
	v_pk_mul_f32 v[4:5], v[4:5], v[20:21] op_sel_hi:[1,0]
	v_pk_mul_f32 v[2:3], v[2:3], v[20:21] op_sel_hi:[1,0]
	v_mov_b32_e32 v19, v18
	v_mov_b32_e32 v20, v18
	v_mov_b32_e32 v21, v18
	v_mov_b32_e32 v22, v18
	v_mov_b32_e32 v23, v18
	v_mov_b32_e32 v24, v18
	v_mov_b32_e32 v25, v18
	v_mov_b32_e32 v26, v18
	v_mov_b32_e32 v27, v18
	v_mov_b32_e32 v28, v18
	v_mov_b32_e32 v29, v18
	v_mov_b32_e32 v30, v18
	v_mov_b32_e32 v31, v18
	v_mov_b32_e32 v32, v18
	v_mov_b32_e32 v33, v18
; #define MFMA(a, b, c) __builtin_amdgcn_mfma_f32_32x32x16_bf16((a), (b), (c), 0, 0, 0)
; template <int N> DI void lgkm_wait() { asm volatile("s_waitcnt lgkmcnt(%0)" :: "i"(N) : "memory"); }
; #define SBAR() __builtin_amdgcn_sched_barrier(0)
;   static DI void run(unsigned vaddr, s16x4 (&lo)[R], s16x4 (&hi)[R], const f32x16& p0, const f32x16& p1, bf16x8& pfc, f32x16 (&o)[4]) {
;     constexpr int issued = (J + R < NF) ? (J + R) : NF;
;     if constexpr ((J & 3) == 0) {
;       if constexpr ((J >> 2) == 0) pfc = pack8<0>(p0);
;       else if constexpr ((J >> 2) == 1) pfc = pack8<8>(p0);
;       else if constexpr ((J >> 2) == 2) pfc = pack8<0>(p1);
;       else pfc = pack8<8>(p1);
;     }
;     lgkm_wait<2 * (issued - J - 1)>(); SBAR();
;     o[J & 3] = MFMA(__builtin_shufflevector(lo[J % R], hi[J % R], 0, 1, 2, 3, 4, 5, 6, 7), pfc, o[J & 3]);
;     SBAR();
;     if (J + R < NF) {
;       constexpr int off = ((J + R) & 3) * 32 * 136 + ((J + R) >> 2) * 32;
;       lo[J % R] = lds_rd64<off>(vaddr); hi[J % R] = lds_rd64<off + 16>(vaddr); SBAR();
;     }
;     if constexpr (J + 1 < NF) PvStep<J + 1, NF, R>::run(vaddr, lo, hi, p0, p1, pfc, o);
;   }
; template <int DQK, int MODE, bool PIPE>
; DI void attn_core(const u16* __restrict__ Qg, const u16* __restrict__ Kg, const u16* __restrict__ Vtg, int ntiles,
;                   int kr_lo, int rs, int r_q, int c_q, int cs, const float* biasL, char* lds, f32x16 (&o)[4], float& l_out, int tid) {
;     ...
;     for (int i = 0; i < 16; ++i) { p0[i] = __builtin_amdgcn_exp2f(p0[i]); p1[i] = __builtin_amdgcn_exp2f(p1[i]); ps += p0[i] + p1[i]; }
;     l += ps;
;     const char* vb = lds + (t & 1) * A_BUF + A_VOFF + r32 * 136 + h * 8;
;     {
;       bf16x8 pfc;
;       constexpr int R = PV_RING;
;       const unsigned vaddr = (unsigned)(size_t)vb;
;       s16x4 vlo[R], vhi[R];
;       SBAR();
;       vlo[0] = lds_rd64<0>(vaddr); vhi[0] = lds_rd64<16>(vaddr);
;       vlo[1] = lds_rd64<32 * 136>(vaddr); vhi[1] = lds_rd64<32 * 136 + 16>(vaddr);
;       if (R > 2) { vlo[2 % R] = lds_rd64<64 * 136>(vaddr); vhi[2 % R] = lds_rd64<64 * 136 + 16>(vaddr); }
;       if (R > 3) { vlo[3 % R] = lds_rd64<96 * 136>(vaddr); vhi[3 % R] = lds_rd64<96 * 136 + 16>(vaddr); }
;       SBAR();
;       __builtin_amdgcn_s_setprio(1);
;       PvStep<0, 16, R>::run(vaddr, vlo, vhi, p0, p1, pfc, o);
;       __builtin_amdgcn_s_setprio(0);
.LBB0_844:
	v_exp_f32_e32 v82, v82
	v_exp_f32_e32 v98, v98
	v_exp_f32_e32 v83, v83
	v_exp_f32_e32 v99, v99
	v_exp_f32_e32 v84, v84
	v_exp_f32_e32 v100, v100
	v_exp_f32_e32 v85, v85
	v_exp_f32_e32 v101, v101
	v_exp_f32_e32 v86, v86
	v_exp_f32_e32 v102, v102
	v_exp_f32_e32 v87, v87
	v_exp_f32_e32 v103, v103
	v_exp_f32_e32 v88, v88
	v_exp_f32_e32 v104, v104
	v_exp_f32_e32 v89, v89
	v_exp_f32_e32 v105, v105
	v_exp_f32_e32 v90, v90
	v_exp_f32_e32 v106, v106
	v_exp_f32_e32 v91, v91
	v_exp_f32_e32 v107, v107
	v_exp_f32_e32 v92, v92
	v_exp_f32_e32 v108, v108
	v_exp_f32_e32 v93, v93
	v_exp_f32_e32 v109, v109
	v_exp_f32_e32 v94, v94
	v_exp_f32_e32 v110, v110
	v_exp_f32_e32 v95, v95
	v_exp_f32_e32 v111, v111
	v_exp_f32_e32 v96, v96
	v_exp_f32_e32 v112, v112
	v_exp_f32_e32 v97, v97
	v_exp_f32_e32 v113, v113
	v_add_u32_e32 v177, s15, v168
	v_add3_u32 v177, v177, v166, s33
	ds_read_b64 v[216:217], v177 offset:0
	ds_read_b64 v[218:219], v177 offset:16
	ds_read_b64 v[220:221], v177 offset:0x1100
	ds_read_b64 v[222:223], v177 offset:0x1110
	ds_read_b64 v[224:225], v177 offset:0x2200
	ds_read_b64 v[226:227], v177 offset:0x2210
	ds_read_b64 v[228:229], v177 offset:0x3300
	ds_read_b64 v[230:231], v177 offset:0x3310
	s_waitcnt lgkmcnt(4)
	v_cvt_pk_bf16_f32 v232, v82, v83
	v_cvt_pk_bf16_f32 v233, v84, v85
	v_cvt_pk_bf16_f32 v234, v86, v87
	v_cvt_pk_bf16_f32 v235, v88, v89
	s_nop 1
	v_mfma_f32_32x32x16_bf16 v[66:81], v[216:219], v[232:235], v[66:81]
	ds_read_b64 v[216:217], v177 offset:32
	ds_read_b64 v[218:219], v177 offset:48
	v_mfma_f32_32x32x16_bf16 v[50:65], v[220:223], v[232:235], v[50:65]
	ds_read_b64 v[220:221], v177 offset:0x1120
	ds_read_b64 v[222:223], v177 offset:0x1130
	s_waitcnt lgkmcnt(4)
	v_mfma_f32_32x32x16_bf16 v[34:49], v[224:227], v[232:235], v[34:49]
	ds_read_b64 v[224:225], v177 offset:0x2220
	ds_read_b64 v[226:227], v177 offset:0x2230
	v_mfma_f32_32x32x16_bf16 v[2:17], v[228:231], v[232:235], v[2:17]
	ds_read_b64 v[228:229], v177 offset:0x3320
	ds_read_b64 v[230:231], v177 offset:0x3330
	s_waitcnt lgkmcnt(4)
	v_cvt_pk_bf16_f32 v232, v90, v91
	v_cvt_pk_bf16_f32 v233, v92, v93
	v_cvt_pk_bf16_f32 v234, v94, v95
	v_cvt_pk_bf16_f32 v235, v96, v97
	s_nop 1
	v_mfma_f32_32x32x16_bf16 v[66:81], v[216:219], v[232:235], v[66:81]
	ds_read_b64 v[216:217], v177 offset:64
	ds_read_b64 v[218:219], v177 offset:0x50
	v_mfma_f32_32x32x16_bf16 v[50:65], v[220:223], v[232:235], v[50:65]
	ds_read_b64 v[220:221], v177 offset:0x1140
	ds_read_b64 v[222:223], v177 offset:0x1150
	s_waitcnt lgkmcnt(4)
	v_mfma_f32_32x32x16_bf16 v[34:49], v[224:227], v[232:235], v[34:49]
	ds_read_b64 v[224:225], v177 offset:0x2240
	ds_read_b64 v[226:227], v177 offset:0x2250
	v_mfma_f32_32x32x16_bf16 v[2:17], v[228:231], v[232:235], v[2:17]
	ds_read_b64 v[228:229], v177 offset:0x3340
	ds_read_b64 v[230:231], v177 offset:0x3350
	s_waitcnt lgkmcnt(4)
	v_cvt_pk_bf16_f32 v232, v98, v99
	v_cvt_pk_bf16_f32 v233, v100, v101
	v_cvt_pk_bf16_f32 v234, v102, v103
	v_cvt_pk_bf16_f32 v235, v104, v105
	s_nop 1
	v_mfma_f32_32x32x16_bf16 v[66:81], v[216:219], v[232:235], v[66:81]
	ds_read_b64 v[216:217], v177 offset:0x60
	ds_read_b64 v[218:219], v177 offset:0x70
	v_mfma_f32_32x32x16_bf16 v[50:65], v[220:223], v[232:235], v[50:65]
	ds_read_b64 v[220:221], v177 offset:0x1160
	ds_read_b64 v[222:223], v177 offset:0x1170
	s_waitcnt lgkmcnt(4)
	v_mfma_f32_32x32x16_bf16 v[34:49], v[224:227], v[232:235], v[34:49]
	ds_read_b64 v[224:225], v177 offset:0x2260
	ds_read_b64 v[226:227], v177 offset:0x2270
	v_mfma_f32_32x32x16_bf16 v[2:17], v[228:231], v[232:235], v[2:17]
	ds_read_b64 v[228:229], v177 offset:0x3360
	ds_read_b64 v[230:231], v177 offset:0x3370
	s_waitcnt lgkmcnt(4)
	v_cvt_pk_bf16_f32 v232, v106, v107
	v_cvt_pk_bf16_f32 v233, v108, v109
	v_cvt_pk_bf16_f32 v234, v110, v111
	v_cvt_pk_bf16_f32 v235, v112, v113
	s_nop 1
	v_mfma_f32_32x32x16_bf16 v[66:81], v[216:219], v[232:235], v[66:81]
	v_mfma_f32_32x32x16_bf16 v[50:65], v[220:223], v[232:235], v[50:65]
	s_waitcnt lgkmcnt(0)
	v_mfma_f32_32x32x16_bf16 v[34:49], v[224:227], v[232:235], v[34:49]
	v_mfma_f32_32x32x16_bf16 v[2:17], v[228:231], v[232:235], v[2:17]
	s_andn2_b64 vcc, exec, s[0:1]
	s_cbranch_vccnz .LBB0_846
	s_bitcmp1_b32 s14, 0
	s_cselect_b32 s0, 0xa800, 0
	v_add_u32_e32 v177, s0, v143
	s_waitcnt vmcnt(0)
	ds_write_b128 v177, v[138:141]

; template <int DQK, int MODE, bool PIPE>
; DI void attn_core(const u16* __restrict__ Qg, const u16* __restrict__ Kg, const u16* __restrict__ Vtg, int ntiles,
;                   int kr_lo, int rs, int r_q, int c_q, int cs, const float* biasL, char* lds, f32x16 (&o)[4], float& l_out, int tid) {
;     ...
;     const u16* qrow = Qg + (size_t)(wid * 32 + r32) * DQK + h * 8;
; #pragma unroll
;     for (int ks = 0; ks < NKS; ++ks) qf[ks] = *(const bf16x8*)(qrow + ks * 16);
;   }
; #pragma unroll
;   for (int d = 0; d < 4; ++d)
; #pragma unroll
;     for (int i = 0; i < 16; ++i) o[d][i] = 0.f;
;   float m = 0.f, l = 0.f;
;   constexpr bool NEGM = (MODE == 0 && DQK == 64);
;   f32x16 negm;
; #pragma unroll
;   for (int i = 0; i < 16; ++i) negm[i] = 0.f;
;   u32x4 rk[KPT], rv[2];
;   auto keystart = [&](int t) -> int { if (MODE == 1 && t >= 4) return NCTX + 64 * (kr_lo + t - 4); return 64 * t; };
;   auto gloadK = [&](int t) {
;     const u16* kp = Kg + (size_t)keystart(t) * DQK;
; #pragma unroll
;     for (int j = 0; j < KPT; ++j) rk[j] = *(const u32x4*)(kp + (size_t)(tid + NT_ * j) * 8);
;   };
;   auto gloadV = [&](int t) {
;     const int key0 = keystart(t);
; #pragma unroll
;     for (int j = 0; j < 2; ++j) { const int q = tid + NT_ * j; rv[j] = *(const u32x4*)(Vtg + (size_t)(q >> 3) * NR + key0 + (q & 7) * 8); }
;   };
;     ...
;       float* d1 = p.D1 + ((size_t)blockIdx.x * 256 + wid * 32 + r32) * 128 + 4 * h;
;       { const float inv = 1.f / l;
; #pragma unroll
;         for (int d = 0; d < 4; ++d)
; #pragma unroll
;           for (int g = 0; g < 4; ++g)
;             *(float4*)(d1 + 32 * d + 8 * g) = make_float4(o[d][4 * g] * inv, o[d][4 * g + 1] * inv, o[d][4 * g + 2] * inv, o[d][4 * g + 3] * inv); }
;       attn_core<64, 0, false>(p.Qd + ((size_t)(hd * 2 + 1) * NR + q0) * 64, p.Kd + (size_t)(hd * 2 + 1) * NR * 64, Vt, nt, 0, 0, 0, 0, 0, biasL, lds, o, l, tid);
.LBB0_850:
	v_and_b32_e32 v19, 64, v189
	v_xor_b32_e32 v18, 32, v189
	v_add_u32_e32 v19, 64, v19
	v_cmp_lt_i32_e32 vcc, v18, v19
	v_lshlrev_b32_e32 v144, 5, v197
	v_readlane_b32 s0, v254, 1
	v_cndmask_b32_e32 v18, v189, v18, vcc
	v_lshlrev_b32_e32 v162, 2, v18
	ds_bpermute_b32 v18, v162, v176
	v_ashrrev_i32_e32 v145, 31, v144
	v_readlane_b32 s1, v254, 2
	s_or_b32 s6, s12, 1
	v_readlane_b32 s16, v252, 6
	s_waitcnt lgkmcnt(0)
	v_add_f32_e32 v20, v176, v18
	v_lshl_add_u64 v[18:19], s[0:1], 0, v[144:145]
	v_div_scale_f32 v21, s[0:1], v20, v20, 1.0
	v_rcp_f32_e32 v22, v21
	v_or_b32_e32 v18, v18, v193
	v_readlane_b32 s0, v252, 0
	v_lshlrev_b64 v[18:19], 9, v[18:19]
	v_readlane_b32 s1, v252, 1
	v_readlane_b32 s18, v252, 8
	v_readlane_b32 s19, v252, 9
	v_lshl_add_u64 v[18:19], s[0:1], 0, v[18:19]
	v_lshl_add_u64 v[150:151], v[18:19], 0, v[0:1]
	v_fma_f32 v18, -v21, v22, 1.0
	v_fmac_f32_e32 v22, v18, v22
	v_div_scale_f32 v18, vcc, 1.0, v20, 1.0
	v_mul_f32_e32 v19, v18, v22
	v_fma_f32 v23, -v21, v19, v18
	v_fmac_f32_e32 v19, v23, v22
	v_fma_f32 v18, -v21, v19, v18
	v_div_fmas_f32 v18, v18, v22, v19
	v_div_fixup_f32 v22, v18, v20, 1.0
	v_pk_mul_f32 v[18:19], v[66:67], v[22:23] op_sel_hi:[1,0]
	v_pk_mul_f32 v[20:21], v[68:69], v[22:23] op_sel_hi:[1,0]
	global_store_dwordx4 v[150:151], v[18:21], off
	s_mul_i32 s0, s6, 0x4100
	s_mul_hi_i32 s1, s6, 0x4100
	v_pk_mul_f32 v[18:19], v[70:71], v[22:23] op_sel_hi:[1,0]
	v_pk_mul_f32 v[20:21], v[72:73], v[22:23] op_sel_hi:[1,0]
	global_store_dwordx4 v[150:151], v[18:21], off offset:32
	s_add_u32 s0, s0, s9
	s_addc_u32 s1, s1, s11
	v_pk_mul_f32 v[18:19], v[74:75], v[22:23] op_sel_hi:[1,0]
	v_pk_mul_f32 v[20:21], v[76:77], v[22:23] op_sel_hi:[1,0]
	global_store_dwordx4 v[150:151], v[18:21], off offset:64
	s_lshl_b64 s[0:1], s[0:1], 7
	v_pk_mul_f32 v[2:3], v[2:3], v[22:23] op_sel_hi:[1,0]
	v_pk_mul_f32 v[18:19], v[78:79], v[22:23] op_sel_hi:[1,0]
	v_pk_mul_f32 v[20:21], v[80:81], v[22:23] op_sel_hi:[1,0]
	global_store_dwordx4 v[150:151], v[18:21], off offset:96
	v_pk_mul_f32 v[4:5], v[4:5], v[22:23] op_sel_hi:[1,0]
	s_add_u32 s0, s18, s0
	v_pk_mul_f32 v[18:19], v[50:51], v[22:23] op_sel_hi:[1,0]
	v_pk_mul_f32 v[20:21], v[52:53], v[22:23] op_sel_hi:[1,0]
	global_store_dwordx4 v[150:151], v[18:21], off offset:128
	global_store_dwordx4 v[150:151], v[2:5], off offset:384
	v_readlane_b32 s20, v252, 10
	v_pk_mul_f32 v[18:19], v[54:55], v[22:23] op_sel_hi:[1,0]
	v_pk_mul_f32 v[20:21], v[56:57], v[22:23] op_sel_hi:[1,0]
	global_store_dwordx4 v[150:151], v[18:21], off offset:160
	v_pk_mul_f32 v[2:3], v[6:7], v[22:23] op_sel_hi:[1,0]
	v_pk_mul_f32 v[4:5], v[8:9], v[22:23] op_sel_hi:[1,0]
	v_pk_mul_f32 v[18:19], v[58:59], v[22:23] op_sel_hi:[1,0]
	v_pk_mul_f32 v[20:21], v[60:61], v[22:23] op_sel_hi:[1,0]
	global_store_dwordx4 v[150:151], v[18:21], off offset:192
	s_addc_u32 s1, s19, s1
	s_mul_hi_i32 s7, s6, 0x208000
	v_pk_mul_f32 v[18:19], v[62:63], v[22:23] op_sel_hi:[1,0]
	v_pk_mul_f32 v[20:21], v[64:65], v[22:23] op_sel_hi:[1,0]
	global_store_dwordx4 v[150:151], v[18:21], off offset:224
	s_mul_i32 s6, s6, 0x208000
	global_store_dwordx4 v[150:151], v[2:5], off offset:416
	v_pk_mul_f32 v[18:19], v[34:35], v[22:23] op_sel_hi:[1,0]
	v_pk_mul_f32 v[20:21], v[36:37], v[22:23] op_sel_hi:[1,0]
	global_store_dwordx4 v[150:151], v[18:21], off offset:256
	v_pk_mul_f32 v[2:3], v[10:11], v[22:23] op_sel_hi:[1,0]
	v_pk_mul_f32 v[4:5], v[12:13], v[22:23] op_sel_hi:[1,0]
	v_pk_mul_f32 v[18:19], v[38:39], v[22:23] op_sel_hi:[1,0]
	v_pk_mul_f32 v[20:21], v[40:41], v[22:23] op_sel_hi:[1,0]
	global_store_dwordx4 v[150:151], v[18:21], off offset:288
	v_readlane_b32 s21, v252, 11
	s_add_u32 s6, s20, s6
	v_pk_mul_f32 v[18:19], v[42:43], v[22:23] op_sel_hi:[1,0]
	v_pk_mul_f32 v[20:21], v[44:45], v[22:23] op_sel_hi:[1,0]
	global_store_dwordx4 v[150:151], v[18:21], off offset:320
	global_store_dwordx4 v[150:151], v[2:5], off offset:448
	s_addc_u32 s7, s21, s7
	v_pk_mul_f32 v[18:19], v[46:47], v[22:23] op_sel_hi:[1,0]
	v_pk_mul_f32 v[20:21], v[48:49], v[22:23] op_sel_hi:[1,0]
	v_pk_mul_f32 v[2:3], v[14:15], v[22:23] op_sel_hi:[1,0]
	v_pk_mul_f32 v[4:5], v[16:17], v[22:23] op_sel_hi:[1,0]
	global_store_dwordx4 v[150:151], v[18:21], off offset:352
	global_store_dwordx4 v[150:151], v[2:5], off offset:480
	v_lshl_add_u64 v[86:87], s[6:7], 0, v[158:159]
	global_load_dwordx4 v[2:5], v[86:87], off
	global_load_dwordx4 v[6:9], v[154:155], off
	global_load_dwordx4 v[10:13], v[156:157], off
	v_lshlrev_b32_e32 v14, 1, v166
	v_mov_b32_e32 v15, v1
	v_lshl_add_u64 v[16:17], s[0:1], 0, v[152:153]
	v_lshl_add_u64 v[14:15], v[16:17], 0, v[14:15]
	s_movk_i32 s0, 0x2000
	global_load_dwordx4 v[114:117], v[14:15], off
	global_load_dwordx4 v[118:121], v[14:15], off offset:32
	global_load_dwordx4 v[122:125], v[14:15], off offset:64
	global_load_dwordx4 v[126:129], v[14:15], off offset:96
	s_nop 0
	global_load_dwordx4 v[14:17], v[154:155], off offset:128
	global_load_dwordx4 v[18:21], v[156:157], off offset:128
	v_readlane_b32 s17, v252, 7
	v_readlane_b32 s22, v252, 12
	v_readlane_b32 s23, v252, 13
	s_waitcnt vmcnt(8)
	ds_write_b128 v143, v[2:5]
	s_waitcnt vmcnt(7)
	ds_write2_b64 v170, v[6:7], v[8:9] offset1:1
	s_waitcnt vmcnt(6)
	ds_write2_b64 v171, v[10:11], v[12:13] offset1:1
	v_add_co_u32_e32 v2, vcc, s0, v86
	s_nop 1
	v_addc_co_u32_e32 v3, vcc, 0, v87, vcc
	global_load_dwordx4 v[82:85], v[2:3], off
	s_waitcnt lgkmcnt(0)
	s_barrier
; template <int DQK, int MODE, bool PIPE>
; DI void attn_core(const u16* __restrict__ Qg, const u16* __restrict__ Kg, const u16* __restrict__ Vtg, int ntiles,
;                   int kr_lo, int rs, int r_q, int c_q, int cs, const float* biasL, char* lds, f32x16 (&o)[4], float& l_out, int tid) {
;     ...
;     if (MODE == 0) {
;       constexpr int R = 4, NF = 2 * NKS;
;       const unsigned kaddr = (unsigned)(size_t)kb;
;       bf16x8 f[R];
;       SBAR();
;       f[0] = lds_rd128<0>(kaddr); f[1] = lds_rd128<32 * KSTR>(kaddr); f[2] = lds_rd128<32>(kaddr); f[3] = lds_rd128<32 * KSTR + 32>(kaddr);
;       SBAR();
;       __builtin_amdgcn_s_setprio(1);
;       QkStep<DQK, 0, NF, R>::run(kaddr, f, qf, p0, p1, negm);
;       __builtin_amdgcn_s_setprio(0);
;     ...
;     asm volatile("s_nop 7\n\ts_nop 7\n\ts_nop 7" ::: "memory");
;     if (!NEGM && __any(m != 0.f)) {
; #pragma unroll
;       for (int i = 0; i < 16; ++i) {
;         asm("v_sub_f32 %0, %1, %2" : "=v"(p0[i]) : "v"(p0[i]), "v"(m));
;         asm("v_sub_f32 %0, %1, %2" : "=v"(p1[i]) : "v"(p1[i]), "v"(m));
;       }
;     }
;     float tmx;
;     {
;       float u[11];
; #pragma unroll
;       for (int i = 0; i < 5; ++i) {
;         asm("v_max3_f32 %0, %1, %2, %3" : "=v"(u[2 * i]) : "v"(p0[3 * i]), "v"(p0[3 * i + 1]), "v"(p0[3 * i + 2]));
;         asm("v_max3_f32 %0, %1, %2, %3" : "=v"(u[2 * i + 1]) : "v"(p1[3 * i]), "v"(p1[3 * i + 1]), "v"(p1[3 * i + 2]));
;       }
;       asm("v_max3_f32 %0, %1, %2, %3" : "=v"(u[10]) : "v"(p0[15]), "v"(p1[15]), "v"(u[0]));
;       float w0, w1, w2, w3;
;       asm("v_max3_f32 %0, %1, %2, %3" : "=v"(w0) : "v"(u[1]), "v"(u[2]), "v"(u[3]));
;       asm("v_max3_f32 %0, %1, %2, %3" : "=v"(w1) : "v"(u[4]), "v"(u[5]), "v"(u[6]));
;       asm("v_max3_f32 %0, %1, %2, %3" : "=v"(w2) : "v"(u[7]), "v"(u[8]), "v"(u[9]));
;       asm("v_max3_f32 %0, %1, %2, %3" : "=v"(w3) : "v"(u[10]), "v"(w0), "v"(w1));
;       asm("v_max_f32 %0, %1, %2" : "=v"(tmx) : "v"(w2), "v"(w3));
;     }
;     const bool t0 = (t == 0);
;     if (__any(tmx > THR || (t0 && tmx < -THR))) {
;       tmx = fmaxf(tmx, __shfl_xor(tmx, 32));
;       const float delta = t0 ? tmx : fmaxf(tmx, 0.f);
;       const float alpha = __builtin_amdgcn_exp2f(-fmaxf(delta, 0.f));
;       m += delta; l *= alpha;
; #pragma unroll
;       for (int d = 0; d < 4; ++d)
; #pragma unroll
;         for (int i = 0; i < 16; ++i) o[d][i] *= alpha;
	global_load_dwordx4 v[130:133], v[154:155], off offset:256
	global_load_dwordx4 v[134:137], v[156:157], off offset:256
	s_waitcnt vmcnt(4)
	ds_write2_b64 v173, v[14:15], v[16:17] offset1:1
	s_waitcnt vmcnt(3)
	ds_write2_b64 v172, v[18:19], v[20:21] offset1:1
	ds_read_b128 v[2:5], v174 offset:0
	ds_read_b128 v[6:9], v174 offset:0x1200
	ds_read_b128 v[10:13], v174 offset:32
	ds_read_b128 v[14:17], v174 offset:0x1220
	s_waitcnt lgkmcnt(3)
	v_mfma_f32_32x32x16_bf16 v[18:33], v[2:5], v[114:117], 0
	ds_read_b128 v[2:5], v174 offset:64
	s_waitcnt lgkmcnt(3)
	v_mfma_f32_32x32x16_bf16 v[36:51], v[6:9], v[114:117], 0
	ds_read_b128 v[6:9], v174 offset:0x1240
	s_waitcnt lgkmcnt(3)
	v_mfma_f32_32x32x16_bf16 v[18:33], v[10:13], v[118:121], v[18:33]
	ds_read_b128 v[10:13], v174 offset:0x60
	s_waitcnt lgkmcnt(3)
	v_mfma_f32_32x32x16_bf16 v[36:51], v[14:17], v[118:121], v[36:51]
	ds_read_b128 v[14:17], v174 offset:0x1260
	s_waitcnt lgkmcnt(3)
	v_mfma_f32_32x32x16_bf16 v[18:33], v[2:5], v[122:125], v[18:33]
	s_waitcnt lgkmcnt(2)
	v_mfma_f32_32x32x16_bf16 v[36:51], v[6:9], v[122:125], v[36:51]
	s_waitcnt lgkmcnt(1)
	v_mfma_f32_32x32x16_bf16 v[18:33], v[10:13], v[126:129], v[18:33]
	s_waitcnt lgkmcnt(0)
	v_mfma_f32_32x32x16_bf16 v[36:51], v[14:17], v[126:129], v[36:51]
	v_max3_f32 v2, v18, v19, v20
	s_nop 7
	s_nop 7
	s_nop 7
	v_max3_f32 v3, v36, v37, v38
	v_max3_f32 v4, v21, v22, v23
	v_max3_f32 v5, v39, v40, v41
	v_max3_f32 v6, v24, v25, v26
	s_nop 0
	v_max3_f32 v2, v33, v51, v2
	v_max3_f32 v7, v42, v43, v44
	v_max3_f32 v8, v27, v28, v29
	v_max3_f32 v9, v45, v46, v47
	v_max3_f32 v3, v3, v4, v5
	v_max3_f32 v10, v30, v31, v32
	v_max3_f32 v11, v48, v49, v50
	s_nop 0
	v_max3_f32 v4, v6, v7, v8
	v_max3_f32 v5, v9, v10, v11
	s_nop 0
	v_max3_f32 v2, v2, v3, v4
	s_nop 0
	v_max_f32 v2, v5, v2
	s_nop 0
	v_cmp_gt_f32_e64 vcc, |v2|, s66
	s_cbranch_vccz .LBB0_852
	ds_bpermute_b32 v3, v162, v2
	v_max_f32_e32 v2, v2, v2
	s_waitcnt lgkmcnt(0)
	v_max_f32_e32 v3, v3, v3
	v_max_f32_e32 v4, v2, v3
	v_max_f32_e32 v2, 0, v4
	v_exp_f32_e64 v2, -v2
	v_add_f32_e32 v154, 0, v4
	v_pk_add_f32 v[18:19], v[18:19], v[4:5] op_sel_hi:[1,0] neg_lo:[0,1] neg_hi:[0,1]
	v_pk_add_f32 v[36:37], v[36:37], v[4:5] op_sel_hi:[1,0] neg_lo:[0,1] neg_hi:[0,1]
	v_pk_add_f32 v[20:21], v[20:21], v[4:5] op_sel_hi:[1,0] neg_lo:[0,1] neg_hi:[0,1]
	v_pk_add_f32 v[38:39], v[38:39], v[4:5] op_sel_hi:[1,0] neg_lo:[0,1] neg_hi:[0,1]
	v_pk_add_f32 v[22:23], v[22:23], v[4:5] op_sel_hi:[1,0] neg_lo:[0,1] neg_hi:[0,1]
	v_mul_f32_e32 v2, 0, v2
	v_pk_add_f32 v[40:41], v[40:41], v[4:5] op_sel_hi:[1,0] neg_lo:[0,1] neg_hi:[0,1]
	v_pk_add_f32 v[24:25], v[24:25], v[4:5] op_sel_hi:[1,0] neg_lo:[0,1] neg_hi:[0,1]
	v_pk_add_f32 v[42:43], v[42:43], v[4:5] op_sel_hi:[1,0] neg_lo:[0,1] neg_hi:[0,1]
	v_pk_add_f32 v[26:27], v[26:27], v[4:5] op_sel_hi:[1,0] neg_lo:[0,1] neg_hi:[0,1]
	v_pk_add_f32 v[44:45], v[44:45], v[4:5] op_sel_hi:[1,0] neg_lo:[0,1] neg_hi:[0,1]
	v_pk_add_f32 v[28:29], v[28:29], v[4:5] op_sel_hi:[1,0] neg_lo:[0,1] neg_hi:[0,1]
	v_pk_add_f32 v[46:47], v[46:47], v[4:5] op_sel_hi:[1,0] neg_lo:[0,1] neg_hi:[0,1]
	v_pk_add_f32 v[30:31], v[30:31], v[4:5] op_sel_hi:[1,0] neg_lo:[0,1] neg_hi:[0,1]
	v_pk_add_f32 v[48:49], v[48:49], v[4:5] op_sel_hi:[1,0] neg_lo:[0,1] neg_hi:[0,1]
	v_pk_add_f32 v[32:33], v[32:33], v[4:5] op_sel_hi:[1,0] neg_lo:[0,1] neg_hi:[0,1]
	v_pk_add_f32 v[50:51], v[50:51], v[4:5] op_sel_hi:[1,0] neg_lo:[0,1] neg_hi:[0,1]
	v_xor_b32_e32 v34, 0x80000000, v154
	s_branch .LBB0_853

; #define SBAR() __builtin_amdgcn_sched_barrier(0)
; template <int DQK, int MODE, bool PIPE>
; DI void attn_core(const u16* __restrict__ Qg, const u16* __restrict__ Kg, const u16* __restrict__ Vtg, int ntiles,
;                   int kr_lo, int rs, int r_q, int c_q, int cs, const float* biasL, char* lds, f32x16 (&o)[4], float& l_out, int tid) {
;     ...
;     float ps = 0.f;
; #pragma unroll
;     for (int i = 0; i < 16; ++i) { p0[i] = __builtin_amdgcn_exp2f(p0[i]); p1[i] = __builtin_amdgcn_exp2f(p1[i]); ps += p0[i] + p1[i]; }
;     l += ps;
;     const char* vb = lds + (t & 1) * A_BUF + A_VOFF + r32 * 136 + h * 8;
;     {
;       bf16x8 pfc;
;       constexpr int R = PV_RING;
;       const unsigned vaddr = (unsigned)(size_t)vb;
;       s16x4 vlo[R], vhi[R];
;       SBAR();
;       vlo[0] = lds_rd64<0>(vaddr); vhi[0] = lds_rd64<16>(vaddr);
;       vlo[1] = lds_rd64<32 * 136>(vaddr); vhi[1] = lds_rd64<32 * 136 + 16>(vaddr);
;       if (R > 2) { vlo[2 % R] = lds_rd64<64 * 136>(vaddr); vhi[2 % R] = lds_rd64<64 * 136 + 16>(vaddr); }
;       if (R > 3) { vlo[3 % R] = lds_rd64<96 * 136>(vaddr); vhi[3 % R] = lds_rd64<96 * 136 + 16>(vaddr); }
;       SBAR();
;       __builtin_amdgcn_s_setprio(1);
;       PvStep<0, 16, R>::run(vaddr, vlo, vhi, p0, p1, pfc, o);
;       __builtin_amdgcn_s_setprio(0);
;     ...
;   auto step = [&](int t, f32x16& c0, f32x16& c1, f32x16& n0, f32x16& n1) {
;     if (t + 1 < ntiles) swriteV((t + 1) & 1);
;     if (t + 2 < ntiles) gloadV(t + 2);
;     if (PIPE) {
;       if (t + 1 < ntiles) qk(t + 1, n0, n1);
;       sm_pv(t, c0, c1);
;       if (t + 2 < ntiles) swriteK(t & 1);
;       if (t + 3 < ntiles) gloadK(t + 3);
;     } else {
;       if (is_active(t)) { qk(t, c0, c1); sm_pv(t, c0, c1); }
;       if (t + 1 < ntiles) swriteK((t + 1) & 1);
;       if (t + 2 < ntiles) gloadK(t + 2);
;     }
;     __syncthreads();
.LBB0_853:
	v_exp_f32_e32 v35, v18
	v_exp_f32_e32 v138, v36
	v_exp_f32_e32 v56, v19
	v_exp_f32_e32 v139, v37
	v_exp_f32_e32 v57, v20
	v_exp_f32_e32 v140, v38
	v_exp_f32_e32 v58, v21
	v_exp_f32_e32 v141, v39
	v_add_f32_e32 v18, v138, v35
	v_add_f32_e32 v18, 0, v18
	v_add_f32_e32 v19, v139, v56
	v_add_f32_e32 v18, v19, v18
	v_add_f32_e32 v19, v140, v57
	v_add_f32_e32 v18, v19, v18
	v_add_f32_e32 v19, v141, v58
	v_add_f32_e32 v36, v19, v18
	v_exp_f32_e32 v19, v22
	v_exp_f32_e32 v21, v40
	v_exp_f32_e32 v18, v23
	v_exp_f32_e32 v20, v41
	v_lshlrev_b32_e32 v145, 2, v195
	v_mov_b32_e32 v3, v2
	v_pk_mov_b32 v[52:53], v[18:19], v[18:19] op_sel:[1,0]
	v_pk_add_f32 v[22:23], v[20:21], v[18:19]
	v_exp_f32_e32 v19, v24
	v_add_f32_e32 v23, v23, v36
	v_pk_mov_b32 v[36:37], v[20:21], v[20:21] op_sel:[1,0]
	v_exp_f32_e32 v21, v42
	v_exp_f32_e32 v18, v25
	v_exp_f32_e32 v20, v43
	v_add_f32_e32 v38, v22, v23
	v_mov_b32_e32 v4, v2
	v_pk_mov_b32 v[54:55], v[18:19], v[18:19] op_sel:[1,0]
	v_pk_add_f32 v[22:23], v[20:21], v[18:19]
	v_pk_mov_b32 v[40:41], v[20:21], v[20:21] op_sel:[1,0]
	v_exp_f32_e32 v19, v26
	v_exp_f32_e32 v21, v44
	v_exp_f32_e32 v18, v27
	v_exp_f32_e32 v20, v45
	v_add_f32_e32 v23, v23, v38
	v_add_f32_e32 v24, v22, v23
	v_pk_mov_b32 v[104:105], v[18:19], v[18:19] op_sel:[1,0]
	v_pk_add_f32 v[22:23], v[20:21], v[18:19]
	v_pk_mov_b32 v[38:39], v[20:21], v[20:21] op_sel:[1,0]
	v_exp_f32_e32 v19, v28
	v_exp_f32_e32 v21, v46
	v_exp_f32_e32 v18, v29
	v_exp_f32_e32 v20, v47
	v_add_f32_e32 v23, v23, v24
	v_add_f32_e32 v24, v22, v23
	v_pk_mov_b32 v[106:107], v[18:19], v[18:19] op_sel:[1,0]
	v_pk_add_f32 v[22:23], v[20:21], v[18:19]
	v_pk_mov_b32 v[42:43], v[20:21], v[20:21] op_sel:[1,0]
	v_exp_f32_e32 v19, v30
	v_exp_f32_e32 v21, v48
	v_exp_f32_e32 v18, v31
	v_exp_f32_e32 v20, v49
	v_add_f32_e32 v23, v23, v24
	v_add_f32_e32 v24, v22, v23
	v_pk_mov_b32 v[48:49], v[18:19], v[18:19] op_sel:[1,0]
	v_pk_add_f32 v[22:23], v[20:21], v[18:19]
	v_pk_mov_b32 v[108:109], v[20:21], v[20:21] op_sel:[1,0]
	v_exp_f32_e32 v19, v32
	v_exp_f32_e32 v21, v50
	v_exp_f32_e32 v18, v33
	v_exp_f32_e32 v20, v51
	v_add_f32_e32 v23, v23, v24
	v_add_f32_e32 v24, v22, v23
	v_pk_mov_b32 v[110:111], v[18:19], v[18:19] op_sel:[1,0]
	v_pk_add_f32 v[22:23], v[20:21], v[18:19]
	v_mov_b32_e32 v5, v2
	v_add_f32_e32 v23, v23, v24
	v_add_f32_e32 v18, v22, v23
	v_mov_b32_e32 v6, v2
	v_mov_b32_e32 v7, v2
	v_mov_b32_e32 v8, v2
	v_mov_b32_e32 v9, v2
	v_mov_b32_e32 v10, v2
	v_mov_b32_e32 v11, v2
	v_mov_b32_e32 v12, v2
	v_mov_b32_e32 v13, v2
	v_mov_b32_e32 v14, v2
	v_mov_b32_e32 v15, v2
	v_mov_b32_e32 v16, v2
	v_mov_b32_e32 v17, v2
	v_add_f32_e32 v155, v2, v18
	v_pk_mov_b32 v[112:113], v[20:21], v[20:21] op_sel:[1,0]
	ds_read_b64 v[18:19], v169 offset:0
	ds_read_b64 v[20:21], v169 offset:16
	ds_read_b64 v[22:23], v169 offset:0x1100
	ds_read_b64 v[24:25], v169 offset:0x1110
	ds_read_b64 v[44:45], v169 offset:0x2200
	ds_read_b64 v[46:47], v169 offset:0x2210
	ds_read_b64 v[88:89], v169 offset:0x3300
	ds_read_b64 v[90:91], v169 offset:0x3310
	s_waitcnt lgkmcnt(6)
	v_cvt_pk_bf16_f32 v92, v35, v56
	v_cvt_pk_bf16_f32 v93, v57, v58
	v_cvt_pk_bf16_f32 v94, v52, v53
	v_cvt_pk_bf16_f32 v95, v54, v55
	s_nop 1
	v_mfma_f32_32x32x16_bf16 v[66:81], v[18:21], v[92:95], v[2:17]
	ds_read_b64 v[96:97], v169 offset:32
	ds_read_b64 v[98:99], v169 offset:48
	s_waitcnt lgkmcnt(6)
	v_mfma_f32_32x32x16_bf16 v[50:65], v[22:25], v[92:95], v[2:17]
	ds_read_b64 v[100:101], v169 offset:0x1120
	ds_read_b64 v[102:103], v169 offset:0x1130
	s_waitcnt lgkmcnt(6)
	v_mfma_f32_32x32x16_bf16 v[18:33], v[44:47], v[92:95], v[2:17]
	ds_read_b64 v[44:45], v169 offset:0x2220
	ds_read_b64 v[46:47], v169 offset:0x2230
	s_waitcnt lgkmcnt(6)
	v_mfma_f32_32x32x16_bf16 v[2:17], v[88:91], v[92:95], v[2:17]
	ds_read_b64 v[88:89], v169 offset:0x3320
	ds_read_b64 v[90:91], v169 offset:0x3330
	s_waitcnt lgkmcnt(6)
	v_cvt_pk_bf16_f32 v92, v104, v105
	v_cvt_pk_bf16_f32 v93, v106, v107
	v_cvt_pk_bf16_f32 v94, v48, v49
	v_cvt_pk_bf16_f32 v95, v110, v111
	s_nop 1
	v_mfma_f32_32x32x16_bf16 v[66:81], v[96:99], v[92:95], v[66:81]
	ds_read_b64 v[96:97], v169 offset:64
	ds_read_b64 v[98:99], v169 offset:0x50
	s_waitcnt lgkmcnt(6)
	v_mfma_f32_32x32x16_bf16 v[50:65], v[100:103], v[92:95], v[50:65]
	ds_read_b64 v[100:101], v169 offset:0x1140
	ds_read_b64 v[102:103], v169 offset:0x1150
	s_waitcnt lgkmcnt(6)
	v_mfma_f32_32x32x16_bf16 v[18:33], v[44:47], v[92:95], v[18:33]
	ds_read_b64 v[44:45], v169 offset:0x2240
	ds_read_b64 v[46:47], v169 offset:0x2250
	s_waitcnt lgkmcnt(6)
	v_mfma_f32_32x32x16_bf16 v[2:17], v[88:91], v[92:95], v[2:17]
	ds_read_b64 v[88:89], v169 offset:0x3340
	ds_read_b64 v[90:91], v169 offset:0x3350
	s_waitcnt lgkmcnt(6)
	v_cvt_pk_bf16_f32 v92, v138, v139
	v_cvt_pk_bf16_f32 v93, v140, v141
	v_cvt_pk_bf16_f32 v94, v36, v37
	v_cvt_pk_bf16_f32 v95, v40, v41
	s_nop 1
	v_mfma_f32_32x32x16_bf16 v[66:81], v[96:99], v[92:95], v[66:81]
	ds_read_b64 v[96:97], v169 offset:0x60
	ds_read_b64 v[98:99], v169 offset:0x70
	s_waitcnt lgkmcnt(6)
	v_mfma_f32_32x32x16_bf16 v[50:65], v[100:103], v[92:95], v[50:65]
	ds_read_b64 v[100:101], v169 offset:0x1160
	ds_read_b64 v[102:103], v169 offset:0x1170
	s_waitcnt lgkmcnt(6)
	v_mfma_f32_32x32x16_bf16 v[18:33], v[44:47], v[92:95], v[18:33]
	ds_read_b64 v[44:45], v169 offset:0x2260
	ds_read_b64 v[46:47], v169 offset:0x2270
	s_waitcnt lgkmcnt(6)
	v_mfma_f32_32x32x16_bf16 v[2:17], v[88:91], v[92:95], v[2:17]
	ds_read_b64 v[88:89], v169 offset:0x3360
	ds_read_b64 v[90:91], v169 offset:0x3370
	s_waitcnt lgkmcnt(6)
	v_cvt_pk_bf16_f32 v36, v38, v39
	v_cvt_pk_bf16_f32 v37, v42, v43
	v_cvt_pk_bf16_f32 v38, v108, v109
	v_cvt_pk_bf16_f32 v39, v112, v113
	s_nop 1
	v_mfma_f32_32x32x16_bf16 v[66:81], v[96:99], v[36:39], v[66:81]
	s_waitcnt lgkmcnt(4)
	v_mfma_f32_32x32x16_bf16 v[50:65], v[100:103], v[36:39], v[50:65]
	s_waitcnt lgkmcnt(2)
	v_mfma_f32_32x32x16_bf16 v[18:33], v[44:47], v[36:39], v[18:33]
	s_waitcnt lgkmcnt(0)
	v_mfma_f32_32x32x16_bf16 v[2:17], v[88:91], v[36:39], v[2:17]
	v_add_co_u32_e32 v36, vcc, 0x4000, v86
	v_readlane_b32 s0, v254, 36
	s_nop 0
	v_addc_co_u32_e32 v37, vcc, 0, v87, vcc
	global_load_dwordx4 v[138:141], v[36:37], off
	v_readlane_b32 s1, v254, 37
	s_waitcnt vmcnt(3)
	ds_write_b128 v143, v[82:85] offset:43008
	s_waitcnt lgkmcnt(0)
	s_barrier
	v_lshl_add_u64 v[152:153], s[0:1], 0, v[160:161]
	s_mov_b32 s12, 1
	v_mov_b32_e32 v35, v34
	v_mov_b32_e32 v36, v34
	v_mov_b32_e32 v37, v34
	v_mov_b32_e32 v38, v34
	v_mov_b32_e32 v39, v34
	v_mov_b32_e32 v40, v34
	v_mov_b32_e32 v41, v34
	v_mov_b32_e32 v42, v34
	v_mov_b32_e32 v43, v34
	v_mov_b32_e32 v44, v34
	v_mov_b32_e32 v45, v34
	v_mov_b32_e32 v46, v34
	v_mov_b32_e32 v47, v34
	v_mov_b32_e32 v48, v34
	v_mov_b32_e32 v49, v34

; template <int DQK, int MODE, bool PIPE>
; DI void attn_core(const u16* __restrict__ Qg, const u16* __restrict__ Kg, const u16* __restrict__ Vtg, int ntiles,
;                   int kr_lo, int rs, int r_q, int c_q, int cs, const float* biasL, char* lds, f32x16 (&o)[4], float& l_out, int tid) {
;     ...
;   auto qk = [&](int t, f32x16& p0, f32x16& p1) {
;     const char* kb = lds + (t & 1) * A_BUF + r32 * KSTR + h * 16;
;     if (MODE != 0) {
; #pragma unroll
;       for (int i = 0; i < 16; ++i) { p0[i] = 0.f; p1[i] = 0.f; }
;     }
;     if (MODE == 0) {
;       constexpr int R = 4, NF = 2 * NKS;
;       const unsigned kaddr = (unsigned)(size_t)kb;
;       bf16x8 f[R];
;       SBAR();
;       f[0] = lds_rd128<0>(kaddr); f[1] = lds_rd128<32 * KSTR>(kaddr); f[2] = lds_rd128<32>(kaddr); f[3] = lds_rd128<32 * KSTR + 32>(kaddr);
;       SBAR();
;       __builtin_amdgcn_s_setprio(1);
;       QkStep<DQK, 0, NF, R>::run(kaddr, f, qf, p0, p1, negm);
;       __builtin_amdgcn_s_setprio(0);
;     ...
;     asm volatile("s_nop 7\n\ts_nop 7\n\ts_nop 7" ::: "memory");
;     if (!NEGM && __any(m != 0.f)) {
; #pragma unroll
;       for (int i = 0; i < 16; ++i) {
;         asm("v_sub_f32 %0, %1, %2" : "=v"(p0[i]) : "v"(p0[i]), "v"(m));
;         asm("v_sub_f32 %0, %1, %2" : "=v"(p1[i]) : "v"(p1[i]), "v"(m));
;       }
;     }
;     float tmx;
;     {
;       float u[11];
; #pragma unroll
;       for (int i = 0; i < 5; ++i) {
;         asm("v_max3_f32 %0, %1, %2, %3" : "=v"(u[2 * i]) : "v"(p0[3 * i]), "v"(p0[3 * i + 1]), "v"(p0[3 * i + 2]));
;         asm("v_max3_f32 %0, %1, %2, %3" : "=v"(u[2 * i + 1]) : "v"(p1[3 * i]), "v"(p1[3 * i + 1]), "v"(p1[3 * i + 2]));
;       }
;       asm("v_max3_f32 %0, %1, %2, %3" : "=v"(u[10]) : "v"(p0[15]), "v"(p1[15]), "v"(u[0]));
;       float w0, w1, w2, w3;
;       asm("v_max3_f32 %0, %1, %2, %3" : "=v"(w0) : "v"(u[1]), "v"(u[2]), "v"(u[3]));
;       asm("v_max3_f32 %0, %1, %2, %3" : "=v"(w1) : "v"(u[4]), "v"(u[5]), "v"(u[6]));
;       asm("v_max3_f32 %0, %1, %2, %3" : "=v"(w2) : "v"(u[7]), "v"(u[8]), "v"(u[9]));
;       asm("v_max3_f32 %0, %1, %2, %3" : "=v"(w3) : "v"(u[10]), "v"(w0), "v"(w1));
;       asm("v_max_f32 %0, %1, %2" : "=v"(tmx) : "v"(w2), "v"(w3));
;     }
;     const bool t0 = (t == 0);
;     if (__any(tmx > THR || (t0 && tmx < -THR))) {
;       tmx = fmaxf(tmx, __shfl_xor(tmx, 32));
;       const float delta = t0 ? tmx : fmaxf(tmx, 0.f);
.LBB0_858:
	s_bitcmp1_b32 s12, 0
	s_cselect_b32 s12, 0xa800, 0
	v_add3_u32 v160, s12, v167, v0
	ds_read_b128 v[98:101], v160 offset:0
	ds_read_b128 v[156:159], v160 offset:0x1200
	ds_read_b128 v[170:173], v160 offset:32
	ds_read_b128 v[174:177], v160 offset:0x1220
	s_waitcnt lgkmcnt(2)
	v_mfma_f32_32x32x16_bf16 v[82:97], v[98:101], v[114:117], v[34:49]
	ds_read_b128 v[216:219], v160 offset:64
	v_mfma_f32_32x32x16_bf16 v[98:113], v[156:159], v[114:117], v[34:49]
	ds_read_b128 v[156:159], v160 offset:0x1240
	s_waitcnt lgkmcnt(2)
	v_mfma_f32_32x32x16_bf16 v[82:97], v[170:173], v[118:121], v[82:97]
	ds_read_b128 v[170:173], v160 offset:0x60
	v_mfma_f32_32x32x16_bf16 v[98:113], v[174:177], v[118:121], v[98:113]
	ds_read_b128 v[174:177], v160 offset:0x1260
	s_waitcnt lgkmcnt(2)
	v_mfma_f32_32x32x16_bf16 v[82:97], v[216:219], v[122:125], v[82:97]
	v_mfma_f32_32x32x16_bf16 v[98:113], v[156:159], v[122:125], v[98:113]
	s_waitcnt lgkmcnt(0)
	v_mfma_f32_32x32x16_bf16 v[82:97], v[170:173], v[126:129], v[82:97]
	v_mfma_f32_32x32x16_bf16 v[98:113], v[174:177], v[126:129], v[98:113]
	v_max3_f32 v156, v82, v83, v84
	s_nop 7
	s_nop 7
	v_max3_f32 v157, v98, v99, v100
	v_max3_f32 v158, v85, v86, v87
	v_max3_f32 v159, v101, v102, v103
	v_max3_f32 v160, v88, v89, v90
	v_max3_f32 v156, v97, v113, v156
	v_max3_f32 v161, v104, v105, v106
	v_max3_f32 v163, v91, v92, v93
	v_max3_f32 v169, v107, v108, v109
	v_max3_f32 v157, v157, v158, v159
	v_max3_f32 v170, v94, v95, v96
	v_max3_f32 v171, v110, v111, v112
	v_max3_f32 v158, v160, v161, v163
	v_max3_f32 v159, v169, v170, v171
	v_max3_f32 v156, v156, v157, v158
	v_max_f32 v156, v159, v156
	v_cmp_lt_f32_e32 vcc, s66, v156
	s_cbranch_vccz .LBB0_860
	ds_bpermute_b32 v34, v162, v156
	s_waitcnt lgkmcnt(0)
	v_max3_f32 v34, v156, v34, 0
	v_exp_f32_e64 v36, -v34
	v_add_f32_e32 v154, v154, v34
	v_pk_add_f32 v[82:83], v[82:83], v[34:35] op_sel_hi:[1,0] neg_lo:[0,1] neg_hi:[0,1]
	v_pk_add_f32 v[98:99], v[98:99], v[34:35] op_sel_hi:[1,0] neg_lo:[0,1] neg_hi:[0,1]
	v_pk_add_f32 v[84:85], v[84:85], v[34:35] op_sel_hi:[1,0] neg_lo:[0,1] neg_hi:[0,1]
	v_pk_add_f32 v[100:101], v[100:101], v[34:35] op_sel_hi:[1,0] neg_lo:[0,1] neg_hi:[0,1]
	v_pk_add_f32 v[86:87], v[86:87], v[34:35] op_sel_hi:[1,0] neg_lo:[0,1] neg_hi:[0,1]
	v_pk_add_f32 v[102:103], v[102:103], v[34:35] op_sel_hi:[1,0] neg_lo:[0,1] neg_hi:[0,1]
	v_pk_add_f32 v[88:89], v[88:89], v[34:35] op_sel_hi:[1,0] neg_lo:[0,1] neg_hi:[0,1]
	v_pk_add_f32 v[104:105], v[104:105], v[34:35] op_sel_hi:[1,0] neg_lo:[0,1] neg_hi:[0,1]
	v_pk_add_f32 v[90:91], v[90:91], v[34:35] op_sel_hi:[1,0] neg_lo:[0,1] neg_hi:[0,1]
	v_pk_add_f32 v[106:107], v[106:107], v[34:35] op_sel_hi:[1,0] neg_lo:[0,1] neg_hi:[0,1]
	v_pk_add_f32 v[92:93], v[92:93], v[34:35] op_sel_hi:[1,0] neg_lo:[0,1] neg_hi:[0,1]
	v_pk_add_f32 v[108:109], v[108:109], v[34:35] op_sel_hi:[1,0] neg_lo:[0,1] neg_hi:[0,1]
	v_pk_add_f32 v[94:95], v[94:95], v[34:35] op_sel_hi:[1,0] neg_lo:[0,1] neg_hi:[0,1]
	v_pk_add_f32 v[110:111], v[110:111], v[34:35] op_sel_hi:[1,0] neg_lo:[0,1] neg_hi:[0,1]
	v_pk_add_f32 v[96:97], v[96:97], v[34:35] op_sel_hi:[1,0] neg_lo:[0,1] neg_hi:[0,1]
	v_pk_add_f32 v[112:113], v[112:113], v[34:35] op_sel_hi:[1,0] neg_lo:[0,1] neg_hi:[0,1]
	v_xor_b32_e32 v34, 0x80000000, v154
	v_mul_f32_e32 v155, v155, v36
	v_pk_mul_f32 v[80:81], v[80:81], v[36:37] op_sel_hi:[1,0]
	v_pk_mul_f32 v[78:79], v[78:79], v[36:37] op_sel_hi:[1,0]
	v_pk_mul_f32 v[76:77], v[76:77], v[36:37] op_sel_hi:[1,0]
	v_pk_mul_f32 v[74:75], v[74:75], v[36:37] op_sel_hi:[1,0]
	v_pk_mul_f32 v[72:73], v[72:73], v[36:37] op_sel_hi:[1,0]
	v_pk_mul_f32 v[70:71], v[70:71], v[36:37] op_sel_hi:[1,0]
	v_pk_mul_f32 v[68:69], v[68:69], v[36:37] op_sel_hi:[1,0]
	v_pk_mul_f32 v[66:67], v[66:67], v[36:37] op_sel_hi:[1,0]
	v_pk_mul_f32 v[64:65], v[64:65], v[36:37] op_sel_hi:[1,0]
	v_pk_mul_f32 v[62:63], v[62:63], v[36:37] op_sel_hi:[1,0]
	v_pk_mul_f32 v[60:61], v[60:61], v[36:37] op_sel_hi:[1,0]
	v_pk_mul_f32 v[58:59], v[58:59], v[36:37] op_sel_hi:[1,0]
	v_pk_mul_f32 v[56:57], v[56:57], v[36:37] op_sel_hi:[1,0]
	v_pk_mul_f32 v[54:55], v[54:55], v[36:37] op_sel_hi:[1,0]
	v_pk_mul_f32 v[52:53], v[52:53], v[36:37] op_sel_hi:[1,0]
	v_pk_mul_f32 v[50:51], v[50:51], v[36:37] op_sel_hi:[1,0]
	v_pk_mul_f32 v[32:33], v[32:33], v[36:37] op_sel_hi:[1,0]
	v_pk_mul_f32 v[30:31], v[30:31], v[36:37] op_sel_hi:[1,0]
	v_pk_mul_f32 v[28:29], v[28:29], v[36:37] op_sel_hi:[1,0]
	v_pk_mul_f32 v[26:27], v[26:27], v[36:37] op_sel_hi:[1,0]
	v_pk_mul_f32 v[24:25], v[24:25], v[36:37] op_sel_hi:[1,0]
	v_pk_mul_f32 v[22:23], v[22:23], v[36:37] op_sel_hi:[1,0]
	v_pk_mul_f32 v[20:21], v[20:21], v[36:37] op_sel_hi:[1,0]
	v_pk_mul_f32 v[18:19], v[18:19], v[36:37] op_sel_hi:[1,0]
	v_pk_mul_f32 v[16:17], v[16:17], v[36:37] op_sel_hi:[1,0]
	v_pk_mul_f32 v[14:15], v[14:15], v[36:37] op_sel_hi:[1,0]
	v_pk_mul_f32 v[12:13], v[12:13], v[36:37] op_sel_hi:[1,0]
	v_pk_mul_f32 v[10:11], v[10:11], v[36:37] op_sel_hi:[1,0]
	v_pk_mul_f32 v[8:9], v[8:9], v[36:37] op_sel_hi:[1,0]
	v_pk_mul_f32 v[6:7], v[6:7], v[36:37] op_sel_hi:[1,0]
	v_pk_mul_f32 v[4:5], v[4:5], v[36:37] op_sel_hi:[1,0]
	v_pk_mul_f32 v[2:3], v[2:3], v[36:37] op_sel_hi:[1,0]
	v_mov_b32_e32 v35, v34
	v_mov_b32_e32 v36, v34
	v_mov_b32_e32 v37, v34
	v_mov_b32_e32 v38, v34
	v_mov_b32_e32 v39, v34
	v_mov_b32_e32 v40, v34
	v_mov_b32_e32 v41, v34
	v_mov_b32_e32 v42, v34
	v_mov_b32_e32 v43, v34
	v_mov_b32_e32 v44, v34
	v_mov_b32_e32 v45, v34
	v_mov_b32_e32 v46, v34
	v_mov_b32_e32 v47, v34
	v_mov_b32_e32 v48, v34
	v_mov_b32_e32 v49, v34
; #define SBAR() __builtin_amdgcn_sched_barrier(0)
; template <int DQK, int MODE, bool PIPE>
; DI void attn_core(const u16* __restrict__ Qg, const u16* __restrict__ Kg, const u16* __restrict__ Vtg, int ntiles,
;                   int kr_lo, int rs, int r_q, int c_q, int cs, const float* biasL, char* lds, f32x16 (&o)[4], float& l_out, int tid) {
;     ...
;     for (int i = 0; i < 16; ++i) { p0[i] = __builtin_amdgcn_exp2f(p0[i]); p1[i] = __builtin_amdgcn_exp2f(p1[i]); ps += p0[i] + p1[i]; }
;     l += ps;
;     const char* vb = lds + (t & 1) * A_BUF + A_VOFF + r32 * 136 + h * 8;
;     {
;       bf16x8 pfc;
;       constexpr int R = PV_RING;
;       const unsigned vaddr = (unsigned)(size_t)vb;
;       s16x4 vlo[R], vhi[R];
;       SBAR();
;       vlo[0] = lds_rd64<0>(vaddr); vhi[0] = lds_rd64<16>(vaddr);
;       vlo[1] = lds_rd64<32 * 136>(vaddr); vhi[1] = lds_rd64<32 * 136 + 16>(vaddr);
;       if (R > 2) { vlo[2 % R] = lds_rd64<64 * 136>(vaddr); vhi[2 % R] = lds_rd64<64 * 136 + 16>(vaddr); }
;       if (R > 3) { vlo[3 % R] = lds_rd64<96 * 136>(vaddr); vhi[3 % R] = lds_rd64<96 * 136 + 16>(vaddr); }
;       SBAR();
;       __builtin_amdgcn_s_setprio(1);
;       PvStep<0, 16, R>::run(vaddr, vlo, vhi, p0, p1, pfc, o);
;       __builtin_amdgcn_s_setprio(0);
;     ...
;       if (t + 2 < ntiles) swriteK(t & 1);
;       if (t + 3 < ntiles) gloadK(t + 3);
;     } else {
;       if (is_active(t)) { qk(t, c0, c1); sm_pv(t, c0, c1); }
;       if (t + 1 < ntiles) swriteK((t + 1) & 1);
;       if (t + 2 < ntiles) gloadK(t + 2);
.LBB0_860:
	v_exp_f32_e32 v82, v82
	v_exp_f32_e32 v98, v98
	v_exp_f32_e32 v83, v83
	v_exp_f32_e32 v99, v99
	v_exp_f32_e32 v84, v84
	v_exp_f32_e32 v100, v100
	v_exp_f32_e32 v85, v85
	v_exp_f32_e32 v101, v101
	v_exp_f32_e32 v86, v86
	v_exp_f32_e32 v102, v102
	v_exp_f32_e32 v87, v87
	v_exp_f32_e32 v103, v103
	v_exp_f32_e32 v88, v88
	v_exp_f32_e32 v104, v104
	v_exp_f32_e32 v89, v89
	v_exp_f32_e32 v105, v105
	v_exp_f32_e32 v90, v90
	v_exp_f32_e32 v106, v106
	v_exp_f32_e32 v91, v91
	v_exp_f32_e32 v107, v107
	v_exp_f32_e32 v92, v92
	v_exp_f32_e32 v108, v108
	v_exp_f32_e32 v93, v93
	v_exp_f32_e32 v109, v109
	v_exp_f32_e32 v94, v94
	v_exp_f32_e32 v110, v110
	v_exp_f32_e32 v95, v95
	v_exp_f32_e32 v111, v111
	v_exp_f32_e32 v96, v96
	v_exp_f32_e32 v112, v112
	v_exp_f32_e32 v97, v97
	v_exp_f32_e32 v113, v113
	v_add_u32_e32 v156, s12, v168
	v_add3_u32 v160, v156, v166, s33
	ds_read_b64 v[156:157], v160 offset:0
	ds_read_b64 v[158:159], v160 offset:16
	ds_read_b64 v[170:171], v160 offset:0x1100
	ds_read_b64 v[172:173], v160 offset:0x1110
	ds_read_b64 v[174:175], v160 offset:0x2200
	ds_read_b64 v[176:177], v160 offset:0x2210
	ds_read_b64 v[216:217], v160 offset:0x3300
	ds_read_b64 v[218:219], v160 offset:0x3310
	s_waitcnt lgkmcnt(4)
	v_cvt_pk_bf16_f32 v220, v82, v83
	v_cvt_pk_bf16_f32 v221, v84, v85
	v_cvt_pk_bf16_f32 v222, v86, v87
	v_cvt_pk_bf16_f32 v223, v88, v89
	s_nop 1
	v_mfma_f32_32x32x16_bf16 v[66:81], v[156:159], v[220:223], v[66:81]
	ds_read_b64 v[156:157], v160 offset:32
	ds_read_b64 v[158:159], v160 offset:48
	v_mfma_f32_32x32x16_bf16 v[50:65], v[170:173], v[220:223], v[50:65]
	ds_read_b64 v[170:171], v160 offset:0x1120
	ds_read_b64 v[172:173], v160 offset:0x1130
	s_waitcnt lgkmcnt(4)
	v_mfma_f32_32x32x16_bf16 v[18:33], v[174:177], v[220:223], v[18:33]
	ds_read_b64 v[174:175], v160 offset:0x2220
	ds_read_b64 v[176:177], v160 offset:0x2230
	v_mfma_f32_32x32x16_bf16 v[2:17], v[216:219], v[220:223], v[2:17]
	ds_read_b64 v[216:217], v160 offset:0x3320
	ds_read_b64 v[218:219], v160 offset:0x3330
	s_waitcnt lgkmcnt(4)
	v_cvt_pk_bf16_f32 v220, v90, v91
	v_cvt_pk_bf16_f32 v221, v92, v93
	v_cvt_pk_bf16_f32 v222, v94, v95
	v_cvt_pk_bf16_f32 v223, v96, v97
	s_nop 1
	v_mfma_f32_32x32x16_bf16 v[66:81], v[156:159], v[220:223], v[66:81]
	ds_read_b64 v[156:157], v160 offset:64
	ds_read_b64 v[158:159], v160 offset:0x50
	v_mfma_f32_32x32x16_bf16 v[50:65], v[170:173], v[220:223], v[50:65]
	ds_read_b64 v[170:171], v160 offset:0x1140
	ds_read_b64 v[172:173], v160 offset:0x1150
	s_waitcnt lgkmcnt(4)
	v_mfma_f32_32x32x16_bf16 v[18:33], v[174:177], v[220:223], v[18:33]
	ds_read_b64 v[174:175], v160 offset:0x2240
	ds_read_b64 v[176:177], v160 offset:0x2250
	v_mfma_f32_32x32x16_bf16 v[2:17], v[216:219], v[220:223], v[2:17]
	ds_read_b64 v[216:217], v160 offset:0x3340
	ds_read_b64 v[218:219], v160 offset:0x3350
	s_waitcnt lgkmcnt(4)
	v_cvt_pk_bf16_f32 v220, v98, v99
	v_cvt_pk_bf16_f32 v221, v100, v101
	v_cvt_pk_bf16_f32 v222, v102, v103
	v_cvt_pk_bf16_f32 v223, v104, v105
	s_nop 1
	v_mfma_f32_32x32x16_bf16 v[66:81], v[156:159], v[220:223], v[66:81]
	ds_read_b64 v[156:157], v160 offset:0x60
	ds_read_b64 v[158:159], v160 offset:0x70
	v_mfma_f32_32x32x16_bf16 v[50:65], v[170:173], v[220:223], v[50:65]
	ds_read_b64 v[170:171], v160 offset:0x1160
	ds_read_b64 v[172:173], v160 offset:0x1170
	s_waitcnt lgkmcnt(4)
	v_mfma_f32_32x32x16_bf16 v[18:33], v[174:177], v[220:223], v[18:33]
	ds_read_b64 v[174:175], v160 offset:0x2260
	ds_read_b64 v[176:177], v160 offset:0x2270
	v_mfma_f32_32x32x16_bf16 v[2:17], v[216:219], v[220:223], v[2:17]
	ds_read_b64 v[216:217], v160 offset:0x3360
	ds_read_b64 v[218:219], v160 offset:0x3370
	s_waitcnt lgkmcnt(4)
	v_cvt_pk_bf16_f32 v220, v106, v107
	v_cvt_pk_bf16_f32 v221, v108, v109
	v_cvt_pk_bf16_f32 v222, v110, v111
	v_cvt_pk_bf16_f32 v223, v112, v113
	s_nop 1
	v_mfma_f32_32x32x16_bf16 v[66:81], v[156:159], v[220:223], v[66:81]
	v_mfma_f32_32x32x16_bf16 v[50:65], v[170:173], v[220:223], v[50:65]
	s_waitcnt lgkmcnt(0)
	v_mfma_f32_32x32x16_bf16 v[18:33], v[174:177], v[220:223], v[18:33]
	v_mfma_f32_32x32x16_bf16 v[2:17], v[216:219], v[220:223], v[2:17]
	s_andn2_b64 vcc, exec, s[0:1]
	s_cbranch_vccnz .LBB0_862
	s_bitcmp1_b32 s11, 0
	s_cselect_b32 s0, 0xa800, 0
	v_add_u32_e32 v156, s0, v143
	s_waitcnt vmcnt(0)
	ds_write_b128 v156, v[138:141]
